# 3-stage GEMM loops (w2, about/hyout, hyin, abin): next K-step's wait+barrier and first fragment reads moved under the current step's last MFMA group
# baseline (speedup 1.0000x reference)
.LBB0_62:
	s_ashr_i32 s22, s1, 31
	s_lshr_b32 s22, s22, 27
	s_add_i32 s22, s1, s22
	s_and_b32 s23, s22, 0xffffe0
	s_sub_i32 s23, s1, s23
	s_lshl_b32 s40, s23, 8
	s_lshl_b32 s22, s22, 2
	s_ashr_i32 s41, s40, 31
	s_and_b32 s44, s22, 0xffffff80
	v_readlane_b32 s4, v254, 0
	s_ashr_i32 s45, s44, 31
	s_lshl_b64 s[22:23], s[40:41], 11
	v_readlane_b32 s6, v254, 2
	v_readlane_b32 s7, v254, 3
	s_add_u32 s22, s6, s22
	s_addc_u32 s23, s7, s23
	s_lshl_b64 s[4:5], s[44:45], 11
	s_add_u32 s4, s20, s4
	s_addc_u32 s5, s21, s5
	s_waitcnt lgkmcnt(0)
	v_lshrrev_b32_e32 v132, 3, v196
	v_lshrrev_b32_e32 v133, 4, v196
	v_xor_b32_e32 v133, v133, v196
	v_and_b32_e32 v133, 7, v133
	v_lshlrev_b32_e32 v133, 4, v133
	v_lshl_or_b32 v82, v132, 11, v133
	v_add_u32_e32 v83, 0x20000, v82
	v_add_u32_e32 v84, 0x40000, v82
	v_add_u32_e32 v85, 0x60000, v82
	v_add_u32_e32 v132, 0, v140
	v_xor_b32_e32 v132, v132, v141
	v_lshlrev_b32_e32 v132, 4, v132
	v_add3_u32 v86, v150, v132, 0
	v_add3_u32 v128, v151, v132, 0
	v_add_u32_e32 v132, 2, v140
	v_xor_b32_e32 v132, v132, v141
	v_lshlrev_b32_e32 v132, 4, v132
	v_add3_u32 v87, v150, v132, 0
	v_add3_u32 v129, v151, v132, 0
	v_add_u32_e32 v132, 4, v140
	v_xor_b32_e32 v132, v132, v141
	v_lshlrev_b32_e32 v132, 4, v132
	v_add3_u32 v88, v150, v132, 0
	v_add3_u32 v130, v151, v132, 0
	v_add_u32_e32 v132, 6, v140
	v_xor_b32_e32 v132, v132, v141
	v_lshlrev_b32_e32 v132, 4, v132
	v_add3_u32 v89, v150, v132, 0
	v_add3_u32 v131, v151, v132, 0
	v_lshrrev_b32_e32 v132, 6, v196
	v_mov_b64_e32 v[2:3], 0
	v_mov_b64_e32 v[4:5], 0
	v_mov_b64_e32 v[6:7], 0
	v_mov_b64_e32 v[8:9], 0
	v_mov_b64_e32 v[10:11], 0
	v_mov_b64_e32 v[12:13], 0
	v_mov_b64_e32 v[14:15], 0
	v_mov_b64_e32 v[16:17], 0
	v_mov_b64_e32 v[18:19], 0
	v_mov_b64_e32 v[20:21], 0
	v_mov_b64_e32 v[22:23], 0
	v_mov_b64_e32 v[24:25], 0
	v_mov_b64_e32 v[26:27], 0
	v_mov_b64_e32 v[28:29], 0
	v_mov_b64_e32 v[30:31], 0
	v_mov_b64_e32 v[32:33], 0
	v_mov_b64_e32 v[34:35], 0
	v_mov_b64_e32 v[36:37], 0
	v_mov_b64_e32 v[38:39], 0
	v_mov_b64_e32 v[40:41], 0
	v_mov_b64_e32 v[42:43], 0
	v_mov_b64_e32 v[44:45], 0
	v_mov_b64_e32 v[46:47], 0
	v_mov_b64_e32 v[48:49], 0
	v_mov_b64_e32 v[50:51], 0
	v_mov_b64_e32 v[52:53], 0
	v_mov_b64_e32 v[54:55], 0
	v_mov_b64_e32 v[56:57], 0
	v_mov_b64_e32 v[58:59], 0
	v_mov_b64_e32 v[60:61], 0
	v_mov_b64_e32 v[62:63], 0
	v_mov_b64_e32 v[64:65], 0
	v_readfirstlane_b32 s10, v132
	s_lshl_b32 s10, s10, 10
	s_add_i32 s10, s10, 16
	s_add_i32 vcc_hi, s10, 0xc000
	s_mov_b32 m0, s10
	s_nop 0
	global_load_lds_dwordx4 v82, s[22:23]
	s_add_u32 m0, m0, 0x2000
	s_nop 0
	global_load_lds_dwordx4 v83, s[22:23]
	s_add_u32 m0, m0, 0x2000
	s_nop 0
	global_load_lds_dwordx4 v84, s[22:23]
	s_add_u32 m0, m0, 0x2000
	s_nop 0
	global_load_lds_dwordx4 v85, s[22:23]
	s_add_u32 m0, m0, 0x2000
	s_nop 0
	global_load_lds_dwordx4 v82, s[4:5]
	s_add_u32 m0, m0, 0x2000
	s_nop 0
	global_load_lds_dwordx4 v83, s[4:5]
	s_add_u32 s22, s22, 0x80
	s_addc_u32 s23, s23, 0
	s_add_u32 s4, s4, 0x80
	s_addc_u32 s5, s5, 0
	s_mov_b32 m0, vcc_hi
	s_nop 0
	global_load_lds_dwordx4 v82, s[22:23]
	s_add_u32 m0, m0, 0x2000
	s_nop 0
	global_load_lds_dwordx4 v83, s[22:23]
	s_add_u32 m0, m0, 0x2000
	s_nop 0
	global_load_lds_dwordx4 v84, s[22:23]
	s_add_u32 m0, m0, 0x2000
	s_nop 0
	global_load_lds_dwordx4 v85, s[22:23]
	s_add_u32 m0, m0, 0x2000
	s_nop 0
	global_load_lds_dwordx4 v82, s[4:5]
	s_add_u32 m0, m0, 0x2000
	s_nop 0
	global_load_lds_dwordx4 v83, s[4:5]
	s_add_u32 s22, s22, 0x80
	s_addc_u32 s23, s23, 0
	s_add_u32 s4, s4, 0x80
	s_addc_u32 s5, s5, 0
	s_mov_b32 s9, 0
	s_movk_i32 s8, 14
	s_waitcnt vmcnt(6)
	s_barrier
	ds_read_b128 v[154:157], v86
	ds_read_b128 v[158:161], v86 offset:4096
	ds_read_b128 v[162:165], v128 offset:32768
	ds_read_b128 v[166:169], v128 offset:36864
.Lres_loop:
	s_add_i32 vcc_hi, s9, 2
	s_cmp_ge_u32 vcc_hi, 3
	s_cselect_b32 vcc_lo, 3, 0
	s_sub_i32 vcc_hi, vcc_hi, vcc_lo
	s_mul_i32 vcc_hi, vcc_hi, 0xc000
	s_add_i32 vcc_hi, vcc_hi, s10
	ds_read_b128 v[66:69], v87
	ds_read_b128 v[70:73], v87 offset:4096
	ds_read_b128 v[74:77], v129 offset:32768
	ds_read_b128 v[78:81], v129 offset:36864
	s_waitcnt lgkmcnt(4)
	s_setprio 1
	v_mfma_f32_32x32x16_bf16 v[50:65], v[154:157], v[162:165], v[50:65]
	s_mov_b32 m0, vcc_hi
	v_mfma_f32_32x32x16_bf16 v[18:33], v[158:161], v[162:165], v[18:33]
	global_load_lds_dwordx4 v82, s[22:23]
	s_add_u32 m0, m0, 0x2000
	v_mfma_f32_32x32x16_bf16 v[34:49], v[154:157], v[166:169], v[34:49]
	global_load_lds_dwordx4 v83, s[22:23]
	s_add_u32 m0, m0, 0x2000
	v_mfma_f32_32x32x16_bf16 v[2:17], v[158:161], v[166:169], v[2:17]
	global_load_lds_dwordx4 v84, s[22:23]
	s_add_u32 m0, m0, 0x2000
	s_nop 0
	global_load_lds_dwordx4 v85, s[22:23]
	s_add_u32 m0, m0, 0x2000
	s_nop 0
	global_load_lds_dwordx4 v82, s[4:5]
	s_add_u32 m0, m0, 0x2000
	s_nop 0
	global_load_lds_dwordx4 v83, s[4:5]
	s_add_u32 s22, s22, 0x80
	s_addc_u32 s23, s23, 0
	s_add_u32 s4, s4, 0x80
	s_addc_u32 s5, s5, 0
	s_setprio 0
	ds_read_b128 v[154:157], v88
	ds_read_b128 v[158:161], v88 offset:4096
	ds_read_b128 v[162:165], v130 offset:32768
	ds_read_b128 v[166:169], v130 offset:36864
	s_waitcnt lgkmcnt(4)
	s_setprio 1
	v_mfma_f32_32x32x16_bf16 v[50:65], v[66:69], v[74:77], v[50:65]
	v_mfma_f32_32x32x16_bf16 v[18:33], v[70:73], v[74:77], v[18:33]
	v_mfma_f32_32x32x16_bf16 v[34:49], v[66:69], v[78:81], v[34:49]
	v_mfma_f32_32x32x16_bf16 v[2:17], v[70:73], v[78:81], v[2:17]
	s_setprio 0
	ds_read_b128 v[66:69], v89
	ds_read_b128 v[70:73], v89 offset:4096
	ds_read_b128 v[74:77], v131 offset:32768
	ds_read_b128 v[78:81], v131 offset:36864
	s_waitcnt lgkmcnt(4)
	s_setprio 1
	v_mfma_f32_32x32x16_bf16 v[50:65], v[154:157], v[162:165], v[50:65]
	v_mfma_f32_32x32x16_bf16 v[18:33], v[158:161], v[162:165], v[18:33]
	v_mfma_f32_32x32x16_bf16 v[34:49], v[154:157], v[166:169], v[34:49]
	v_mfma_f32_32x32x16_bf16 v[2:17], v[158:161], v[166:169], v[2:17]
	s_setprio 0
	s_waitcnt lgkmcnt(0)
	s_waitcnt vmcnt(6)
	s_barrier
	s_add_i32 s9, s9, 1
	s_cmp_eq_u32 s9, 3
	s_cselect_b32 vcc_lo, 0xfffdc000, 0
	s_cselect_b32 s9, 0, s9
	s_add_i32 vcc_lo, vcc_lo, 0xc000
	v_add_u32_e32 v86, vcc_lo, v86
	v_add_u32_e32 v128, vcc_lo, v128
	v_add_u32_e32 v87, vcc_lo, v87
	v_add_u32_e32 v129, vcc_lo, v129
	v_add_u32_e32 v88, vcc_lo, v88
	v_add_u32_e32 v130, vcc_lo, v130
	v_add_u32_e32 v89, vcc_lo, v89
	v_add_u32_e32 v131, vcc_lo, v131
	ds_read_b128 v[154:157], v86
	ds_read_b128 v[158:161], v86 offset:4096
	ds_read_b128 v[162:165], v128 offset:32768
	ds_read_b128 v[166:169], v128 offset:36864
	s_setprio 1
	v_mfma_f32_32x32x16_bf16 v[50:65], v[66:69], v[74:77], v[50:65]
	v_mfma_f32_32x32x16_bf16 v[18:33], v[70:73], v[74:77], v[18:33]
	v_mfma_f32_32x32x16_bf16 v[34:49], v[66:69], v[78:81], v[34:49]
	v_mfma_f32_32x32x16_bf16 v[2:17], v[70:73], v[78:81], v[2:17]
	s_setprio 0
	s_add_i32 s8, s8, -1
	s_cmp_lg_u32 s8, 0
	s_cbranch_scc1 .Lres_loop
	ds_read_b128 v[66:69], v87
	ds_read_b128 v[70:73], v87 offset:4096
	ds_read_b128 v[74:77], v129 offset:32768
	ds_read_b128 v[78:81], v129 offset:36864
	s_waitcnt lgkmcnt(4)
	s_setprio 1
	v_mfma_f32_32x32x16_bf16 v[50:65], v[154:157], v[162:165], v[50:65]
	v_mfma_f32_32x32x16_bf16 v[18:33], v[158:161], v[162:165], v[18:33]
	v_mfma_f32_32x32x16_bf16 v[34:49], v[154:157], v[166:169], v[34:49]
	v_mfma_f32_32x32x16_bf16 v[2:17], v[158:161], v[166:169], v[2:17]
	s_setprio 0
	ds_read_b128 v[154:157], v88
	ds_read_b128 v[158:161], v88 offset:4096
	ds_read_b128 v[162:165], v130 offset:32768
	ds_read_b128 v[166:169], v130 offset:36864
	s_waitcnt lgkmcnt(4)
	s_setprio 1
	v_mfma_f32_32x32x16_bf16 v[50:65], v[66:69], v[74:77], v[50:65]
	v_mfma_f32_32x32x16_bf16 v[18:33], v[70:73], v[74:77], v[18:33]
	v_mfma_f32_32x32x16_bf16 v[34:49], v[66:69], v[78:81], v[34:49]
	v_mfma_f32_32x32x16_bf16 v[2:17], v[70:73], v[78:81], v[2:17]
	s_setprio 0
	ds_read_b128 v[66:69], v89
	ds_read_b128 v[70:73], v89 offset:4096
	ds_read_b128 v[74:77], v131 offset:32768
	ds_read_b128 v[78:81], v131 offset:36864
	s_waitcnt lgkmcnt(4)
	s_setprio 1
	v_mfma_f32_32x32x16_bf16 v[50:65], v[154:157], v[162:165], v[50:65]
	v_mfma_f32_32x32x16_bf16 v[18:33], v[158:161], v[162:165], v[18:33]
	v_mfma_f32_32x32x16_bf16 v[34:49], v[154:157], v[166:169], v[34:49]
	v_mfma_f32_32x32x16_bf16 v[2:17], v[158:161], v[166:169], v[2:17]
	s_setprio 0
	s_waitcnt lgkmcnt(0)
	s_waitcnt vmcnt(0)
	s_barrier
	s_add_i32 s9, s9, 1
	s_cmp_eq_u32 s9, 3
	s_cselect_b32 vcc_lo, 0xfffdc000, 0
	s_cselect_b32 s9, 0, s9
	s_add_i32 vcc_lo, vcc_lo, 0xc000
	v_add_u32_e32 v86, vcc_lo, v86
	v_add_u32_e32 v128, vcc_lo, v128
	v_add_u32_e32 v87, vcc_lo, v87
	v_add_u32_e32 v129, vcc_lo, v129
	v_add_u32_e32 v88, vcc_lo, v88
	v_add_u32_e32 v130, vcc_lo, v130
	v_add_u32_e32 v89, vcc_lo, v89
	v_add_u32_e32 v131, vcc_lo, v131
	ds_read_b128 v[154:157], v86
	ds_read_b128 v[158:161], v86 offset:4096
	ds_read_b128 v[162:165], v128 offset:32768
	ds_read_b128 v[166:169], v128 offset:36864
	s_setprio 1
	v_mfma_f32_32x32x16_bf16 v[50:65], v[66:69], v[74:77], v[50:65]
	v_mfma_f32_32x32x16_bf16 v[18:33], v[70:73], v[74:77], v[18:33]
	v_mfma_f32_32x32x16_bf16 v[34:49], v[66:69], v[78:81], v[34:49]
	v_mfma_f32_32x32x16_bf16 v[2:17], v[70:73], v[78:81], v[2:17]
	s_setprio 0
	ds_read_b128 v[66:69], v87
	ds_read_b128 v[70:73], v87 offset:4096
	ds_read_b128 v[74:77], v129 offset:32768
	ds_read_b128 v[78:81], v129 offset:36864
	s_waitcnt lgkmcnt(4)
	s_setprio 1
	v_mfma_f32_32x32x16_bf16 v[50:65], v[154:157], v[162:165], v[50:65]
	v_mfma_f32_32x32x16_bf16 v[18:33], v[158:161], v[162:165], v[18:33]
	v_mfma_f32_32x32x16_bf16 v[34:49], v[154:157], v[166:169], v[34:49]
	v_mfma_f32_32x32x16_bf16 v[2:17], v[158:161], v[166:169], v[2:17]
	s_setprio 0
	ds_read_b128 v[154:157], v88
	ds_read_b128 v[158:161], v88 offset:4096
	ds_read_b128 v[162:165], v130 offset:32768
	ds_read_b128 v[166:169], v130 offset:36864
	s_waitcnt lgkmcnt(4)
	s_setprio 1
	v_mfma_f32_32x32x16_bf16 v[50:65], v[66:69], v[74:77], v[50:65]
	v_mfma_f32_32x32x16_bf16 v[18:33], v[70:73], v[74:77], v[18:33]
	v_mfma_f32_32x32x16_bf16 v[34:49], v[66:69], v[78:81], v[34:49]
	v_mfma_f32_32x32x16_bf16 v[2:17], v[70:73], v[78:81], v[2:17]
	s_setprio 0
	ds_read_b128 v[66:69], v89
	ds_read_b128 v[70:73], v89 offset:4096
	ds_read_b128 v[74:77], v131 offset:32768
	ds_read_b128 v[78:81], v131 offset:36864
	s_waitcnt lgkmcnt(4)
	s_setprio 1
	v_mfma_f32_32x32x16_bf16 v[50:65], v[154:157], v[162:165], v[50:65]
	v_mfma_f32_32x32x16_bf16 v[18:33], v[158:161], v[162:165], v[18:33]
	v_mfma_f32_32x32x16_bf16 v[34:49], v[154:157], v[166:169], v[34:49]
	v_mfma_f32_32x32x16_bf16 v[2:17], v[158:161], v[166:169], v[2:17]
	s_setprio 0
	s_waitcnt lgkmcnt(0)
	s_setprio 1
	v_mfma_f32_32x32x16_bf16 v[50:65], v[66:69], v[74:77], v[50:65]
	v_mfma_f32_32x32x16_bf16 v[18:33], v[70:73], v[74:77], v[18:33]
	v_mfma_f32_32x32x16_bf16 v[34:49], v[66:69], v[78:81], v[34:49]
	v_mfma_f32_32x32x16_bf16 v[2:17], v[70:73], v[78:81], v[2:17]
	s_setprio 0
	s_barrier
	v_readlane_b32 s4, v254, 0
	v_readlane_b32 s5, v254, 1
	v_readlane_b32 s8, v254, 4
	v_readlane_b32 s9, v254, 5
	v_readlane_b32 s10, v254, 6
	v_readlane_b32 s11, v254, 7
	v_readlane_b32 s12, v254, 8
	v_readlane_b32 s13, v254, 9
	v_readlane_b32 s14, v254, 10
	v_readlane_b32 s15, v254, 11
	v_readlane_b32 s16, v254, 12
	v_readlane_b32 s17, v254, 13
	v_readlane_b32 s18, v254, 14
	v_readlane_b32 s19, v254, 15
	s_nop 7
	v_add_u32_e32 v70, s40, v142
	v_add_u32_e32 v66, 0xfffff000, v70
	v_lshrrev_b32_e32 v66, 11, v66
	s_movk_i32 s4, 0x1800
	v_mad_u32_u24 v76, v66, s4, s4
	s_movk_i32 s4, 0xfff
	v_cmp_lt_i32_e32 vcc, s4, v70
	v_or_b32_e32 v68, s44, v143
	s_nop 0
	v_cndmask_b32_e32 v78, 0, v76, vcc
	v_add_u32_e32 v66, v78, v68
	v_ashrrev_i32_e32 v67, 31, v66
	v_lshl_add_u64 v[66:67], v[66:67], 2, s[28:29]
	s_barrier
	global_load_dword v79, v[66:67], off
	v_readlane_b32 s4, v252, 14
	v_ashrrev_i32_e32 v69, 31, v68
	v_readlane_b32 s5, v252, 15
	v_lshl_add_u64 v[66:67], v[68:69], 2, s[42:43]
	v_mov_b32_e32 v77, 0
	s_and_b64 vcc, exec, s[4:5]
	v_mov_b32_e32 v80, 0
	s_cbranch_vccz .LBB0_96
	global_load_dword v80, v[66:67], off

.LBB0_361:
	s_mul_hi_i32 s0, s23, 0x2aaaaaab
	s_lshr_b32 s1, s0, 31
	s_ashr_i32 s0, s0, 1
	s_add_i32 s20, s0, s1
	s_mul_i32 s0, s20, 12
	s_sub_i32 s0, s23, s0
	s_lshl_b32 s40, s0, 8
	s_lshl_b32 s42, s20, 7
	s_ashr_i32 s41, s40, 31
	s_ashr_i32 s43, s42, 31
	s_lshl_b64 s[0:1], s[40:41], 11
	s_lshl_b64 s[20:21], s[42:43], 11
	s_add_u32 s0, s24, s0
	v_readlane_b32 s4, v254, 0
	s_addc_u32 s1, s25, s1
	v_readlane_b32 s6, v254, 2
	v_readlane_b32 s7, v254, 3
	s_add_u32 s20, s6, s20
	s_addc_u32 s21, s7, s21
	s_waitcnt lgkmcnt(0)
	v_lshrrev_b32_e32 v115, 3, v196
	v_lshrrev_b32_e32 v116, 4, v196
	v_xor_b32_e32 v116, v116, v196
	v_and_b32_e32 v116, 7, v116
	v_lshlrev_b32_e32 v116, 4, v116
	v_lshl_or_b32 v98, v115, 11, v116
	v_add_u32_e32 v99, 0x20000, v98
	v_add_u32_e32 v100, 0x40000, v98
	v_add_u32_e32 v101, 0x60000, v98
	v_add_u32_e32 v115, 0, v110
	v_xor_b32_e32 v115, v115, v111
	v_lshlrev_b32_e32 v115, 4, v115
	v_add3_u32 v102, v122, v115, 0
	v_add3_u32 v106, v123, v115, 0
	v_add_u32_e32 v115, 2, v110
	v_xor_b32_e32 v115, v115, v111
	v_lshlrev_b32_e32 v115, 4, v115
	v_add3_u32 v103, v122, v115, 0
	v_add3_u32 v107, v123, v115, 0
	v_add_u32_e32 v115, 4, v110
	v_xor_b32_e32 v115, v115, v111
	v_lshlrev_b32_e32 v115, 4, v115
	v_add3_u32 v104, v122, v115, 0
	v_add3_u32 v108, v123, v115, 0
	v_add_u32_e32 v115, 6, v110
	v_xor_b32_e32 v115, v115, v111
	v_lshlrev_b32_e32 v115, 4, v115
	v_add3_u32 v105, v122, v115, 0
	v_add3_u32 v109, v123, v115, 0
	v_lshrrev_b32_e32 v115, 6, v196
	v_mov_b64_e32 v[2:3], 0
	v_mov_b64_e32 v[4:5], 0
	v_mov_b64_e32 v[6:7], 0
	v_mov_b64_e32 v[8:9], 0
	v_mov_b64_e32 v[10:11], 0
	v_mov_b64_e32 v[12:13], 0
	v_mov_b64_e32 v[14:15], 0
	v_mov_b64_e32 v[16:17], 0
	v_mov_b64_e32 v[18:19], 0
	v_mov_b64_e32 v[20:21], 0
	v_mov_b64_e32 v[22:23], 0
	v_mov_b64_e32 v[24:25], 0
	v_mov_b64_e32 v[26:27], 0
	v_mov_b64_e32 v[28:29], 0
	v_mov_b64_e32 v[30:31], 0
	v_mov_b64_e32 v[32:33], 0
	v_mov_b64_e32 v[34:35], 0
	v_mov_b64_e32 v[36:37], 0
	v_mov_b64_e32 v[38:39], 0
	v_mov_b64_e32 v[40:41], 0
	v_mov_b64_e32 v[42:43], 0
	v_mov_b64_e32 v[44:45], 0
	v_mov_b64_e32 v[46:47], 0
	v_mov_b64_e32 v[48:49], 0
	v_mov_b64_e32 v[50:51], 0
	v_mov_b64_e32 v[52:53], 0
	v_mov_b64_e32 v[54:55], 0
	v_mov_b64_e32 v[56:57], 0
	v_mov_b64_e32 v[58:59], 0
	v_mov_b64_e32 v[60:61], 0
	v_mov_b64_e32 v[62:63], 0
	v_mov_b64_e32 v[64:65], 0
	v_readfirstlane_b32 s30, v115
	s_lshl_b32 s30, s30, 10
	s_add_i32 s30, s30, 16
	s_add_i32 vcc_hi, s30, 0xc000
	s_mov_b32 m0, s30
	s_nop 0
	global_load_lds_dwordx4 v98, s[0:1]
	s_add_u32 m0, m0, 0x2000
	s_nop 0
	global_load_lds_dwordx4 v99, s[0:1]
	s_add_u32 m0, m0, 0x2000
	s_nop 0
	global_load_lds_dwordx4 v100, s[0:1]
	s_add_u32 m0, m0, 0x2000
	s_nop 0
	global_load_lds_dwordx4 v101, s[0:1]
	s_add_u32 m0, m0, 0x2000
	s_nop 0
	global_load_lds_dwordx4 v98, s[20:21]
	s_add_u32 m0, m0, 0x2000
	s_nop 0
	global_load_lds_dwordx4 v99, s[20:21]
	s_add_u32 s0, s0, 0x80
	s_addc_u32 s1, s1, 0
	s_add_u32 s20, s20, 0x80
	s_addc_u32 s21, s21, 0
	s_mov_b32 m0, vcc_hi
	s_nop 0
	global_load_lds_dwordx4 v98, s[0:1]
	s_add_u32 m0, m0, 0x2000
	s_nop 0
	global_load_lds_dwordx4 v99, s[0:1]
	s_add_u32 m0, m0, 0x2000
	s_nop 0
	global_load_lds_dwordx4 v100, s[0:1]
	s_add_u32 m0, m0, 0x2000
	s_nop 0
	global_load_lds_dwordx4 v101, s[0:1]
	s_add_u32 m0, m0, 0x2000
	s_nop 0
	global_load_lds_dwordx4 v98, s[20:21]
	s_add_u32 m0, m0, 0x2000
	s_nop 0
	global_load_lds_dwordx4 v99, s[20:21]
	s_add_u32 s0, s0, 0x80
	s_addc_u32 s1, s1, 0
	s_add_u32 s20, s20, 0x80
	s_addc_u32 s21, s21, 0
	s_mov_b32 s27, 0
	s_movk_i32 s26, 14
	s_waitcnt vmcnt(6)
	s_barrier
	ds_read_b128 v[66:69], v102
	ds_read_b128 v[70:73], v102 offset:4096
	ds_read_b128 v[74:77], v106 offset:32768
	ds_read_b128 v[78:81], v106 offset:36864
.Lhyin_loop:
	s_add_i32 vcc_hi, s27, 2
	s_cmp_ge_u32 vcc_hi, 3
	s_cselect_b32 vcc_lo, 3, 0
	s_sub_i32 vcc_hi, vcc_hi, vcc_lo
	s_mul_i32 vcc_hi, vcc_hi, 0xc000
	s_add_i32 vcc_hi, vcc_hi, s30
	ds_read_b128 v[82:85], v103
	ds_read_b128 v[86:89], v103 offset:4096
	ds_read_b128 v[90:93], v107 offset:32768
	ds_read_b128 v[94:97], v107 offset:36864
	s_waitcnt lgkmcnt(4)
	s_setprio 1
	v_mfma_f32_32x32x16_bf16 v[2:17], v[66:69], v[74:77], v[2:17]
	s_mov_b32 m0, vcc_hi
	v_mfma_f32_32x32x16_bf16 v[18:33], v[70:73], v[74:77], v[18:33]
	global_load_lds_dwordx4 v98, s[0:1]
	s_add_u32 m0, m0, 0x2000
	v_mfma_f32_32x32x16_bf16 v[34:49], v[66:69], v[78:81], v[34:49]
	global_load_lds_dwordx4 v99, s[0:1]
	s_add_u32 m0, m0, 0x2000
	v_mfma_f32_32x32x16_bf16 v[50:65], v[70:73], v[78:81], v[50:65]
	global_load_lds_dwordx4 v100, s[0:1]
	s_add_u32 m0, m0, 0x2000
	s_nop 0
	global_load_lds_dwordx4 v101, s[0:1]
	s_add_u32 m0, m0, 0x2000
	s_nop 0
	global_load_lds_dwordx4 v98, s[20:21]
	s_add_u32 m0, m0, 0x2000
	s_nop 0
	global_load_lds_dwordx4 v99, s[20:21]
	s_add_u32 s0, s0, 0x80
	s_addc_u32 s1, s1, 0
	s_add_u32 s20, s20, 0x80
	s_addc_u32 s21, s21, 0
	s_setprio 0
	ds_read_b128 v[66:69], v104
	ds_read_b128 v[70:73], v104 offset:4096
	ds_read_b128 v[74:77], v108 offset:32768
	ds_read_b128 v[78:81], v108 offset:36864
	s_waitcnt lgkmcnt(4)
	s_setprio 1
	v_mfma_f32_32x32x16_bf16 v[2:17], v[82:85], v[90:93], v[2:17]
	v_mfma_f32_32x32x16_bf16 v[18:33], v[86:89], v[90:93], v[18:33]
	v_mfma_f32_32x32x16_bf16 v[34:49], v[82:85], v[94:97], v[34:49]
	v_mfma_f32_32x32x16_bf16 v[50:65], v[86:89], v[94:97], v[50:65]
	s_setprio 0
	ds_read_b128 v[82:85], v105
	ds_read_b128 v[86:89], v105 offset:4096
	ds_read_b128 v[90:93], v109 offset:32768
	ds_read_b128 v[94:97], v109 offset:36864
	s_waitcnt lgkmcnt(4)
	s_setprio 1
	v_mfma_f32_32x32x16_bf16 v[2:17], v[66:69], v[74:77], v[2:17]
	v_mfma_f32_32x32x16_bf16 v[18:33], v[70:73], v[74:77], v[18:33]
	v_mfma_f32_32x32x16_bf16 v[34:49], v[66:69], v[78:81], v[34:49]
	v_mfma_f32_32x32x16_bf16 v[50:65], v[70:73], v[78:81], v[50:65]
	s_setprio 0
	s_waitcnt lgkmcnt(0)
	s_waitcnt vmcnt(6)
	s_barrier
	s_add_i32 s27, s27, 1
	s_cmp_eq_u32 s27, 3
	s_cselect_b32 vcc_lo, 0xfffdc000, 0
	s_cselect_b32 s27, 0, s27
	s_add_i32 vcc_lo, vcc_lo, 0xc000
	v_add_u32_e32 v102, vcc_lo, v102
	v_add_u32_e32 v106, vcc_lo, v106
	v_add_u32_e32 v103, vcc_lo, v103
	v_add_u32_e32 v107, vcc_lo, v107
	v_add_u32_e32 v104, vcc_lo, v104
	v_add_u32_e32 v108, vcc_lo, v108
	v_add_u32_e32 v105, vcc_lo, v105
	v_add_u32_e32 v109, vcc_lo, v109
	ds_read_b128 v[66:69], v102
	ds_read_b128 v[70:73], v102 offset:4096
	ds_read_b128 v[74:77], v106 offset:32768
	ds_read_b128 v[78:81], v106 offset:36864
	s_setprio 1
	v_mfma_f32_32x32x16_bf16 v[2:17], v[82:85], v[90:93], v[2:17]
	v_mfma_f32_32x32x16_bf16 v[18:33], v[86:89], v[90:93], v[18:33]
	v_mfma_f32_32x32x16_bf16 v[34:49], v[82:85], v[94:97], v[34:49]
	v_mfma_f32_32x32x16_bf16 v[50:65], v[86:89], v[94:97], v[50:65]
	s_setprio 0
	s_add_i32 s26, s26, -1
	s_cmp_lg_u32 s26, 0
	s_cbranch_scc1 .Lhyin_loop
	ds_read_b128 v[82:85], v103
	ds_read_b128 v[86:89], v103 offset:4096
	ds_read_b128 v[90:93], v107 offset:32768
	ds_read_b128 v[94:97], v107 offset:36864
	s_waitcnt lgkmcnt(4)
	s_setprio 1
	v_mfma_f32_32x32x16_bf16 v[2:17], v[66:69], v[74:77], v[2:17]
	v_mfma_f32_32x32x16_bf16 v[18:33], v[70:73], v[74:77], v[18:33]
	v_mfma_f32_32x32x16_bf16 v[34:49], v[66:69], v[78:81], v[34:49]
	v_mfma_f32_32x32x16_bf16 v[50:65], v[70:73], v[78:81], v[50:65]
	s_setprio 0
	ds_read_b128 v[66:69], v104
	ds_read_b128 v[70:73], v104 offset:4096
	ds_read_b128 v[74:77], v108 offset:32768
	ds_read_b128 v[78:81], v108 offset:36864
	s_waitcnt lgkmcnt(4)
	s_setprio 1
	v_mfma_f32_32x32x16_bf16 v[2:17], v[82:85], v[90:93], v[2:17]
	v_mfma_f32_32x32x16_bf16 v[18:33], v[86:89], v[90:93], v[18:33]
	v_mfma_f32_32x32x16_bf16 v[34:49], v[82:85], v[94:97], v[34:49]
	v_mfma_f32_32x32x16_bf16 v[50:65], v[86:89], v[94:97], v[50:65]
	s_setprio 0
	ds_read_b128 v[82:85], v105
	ds_read_b128 v[86:89], v105 offset:4096
	ds_read_b128 v[90:93], v109 offset:32768
	ds_read_b128 v[94:97], v109 offset:36864
	s_waitcnt lgkmcnt(4)
	s_setprio 1
	v_mfma_f32_32x32x16_bf16 v[2:17], v[66:69], v[74:77], v[2:17]
	v_mfma_f32_32x32x16_bf16 v[18:33], v[70:73], v[74:77], v[18:33]
	v_mfma_f32_32x32x16_bf16 v[34:49], v[66:69], v[78:81], v[34:49]
	v_mfma_f32_32x32x16_bf16 v[50:65], v[70:73], v[78:81], v[50:65]
	s_setprio 0
	s_waitcnt lgkmcnt(0)
	s_waitcnt vmcnt(0)
	s_barrier
	s_add_i32 s27, s27, 1
	s_cmp_eq_u32 s27, 3
	s_cselect_b32 vcc_lo, 0xfffdc000, 0
	s_cselect_b32 s27, 0, s27
	s_add_i32 vcc_lo, vcc_lo, 0xc000
	v_add_u32_e32 v102, vcc_lo, v102
	v_add_u32_e32 v106, vcc_lo, v106
	v_add_u32_e32 v103, vcc_lo, v103
	v_add_u32_e32 v107, vcc_lo, v107
	v_add_u32_e32 v104, vcc_lo, v104
	v_add_u32_e32 v108, vcc_lo, v108
	v_add_u32_e32 v105, vcc_lo, v105
	v_add_u32_e32 v109, vcc_lo, v109
	ds_read_b128 v[66:69], v102
	ds_read_b128 v[70:73], v102 offset:4096
	ds_read_b128 v[74:77], v106 offset:32768
	ds_read_b128 v[78:81], v106 offset:36864
	s_setprio 1
	v_mfma_f32_32x32x16_bf16 v[2:17], v[82:85], v[90:93], v[2:17]
	v_mfma_f32_32x32x16_bf16 v[18:33], v[86:89], v[90:93], v[18:33]
	v_mfma_f32_32x32x16_bf16 v[34:49], v[82:85], v[94:97], v[34:49]
	v_mfma_f32_32x32x16_bf16 v[50:65], v[86:89], v[94:97], v[50:65]
	s_setprio 0
	ds_read_b128 v[82:85], v103
	ds_read_b128 v[86:89], v103 offset:4096
	ds_read_b128 v[90:93], v107 offset:32768
	ds_read_b128 v[94:97], v107 offset:36864
	s_waitcnt lgkmcnt(4)
	s_setprio 1
	v_mfma_f32_32x32x16_bf16 v[2:17], v[66:69], v[74:77], v[2:17]
	v_mfma_f32_32x32x16_bf16 v[18:33], v[70:73], v[74:77], v[18:33]
	v_mfma_f32_32x32x16_bf16 v[34:49], v[66:69], v[78:81], v[34:49]
	v_mfma_f32_32x32x16_bf16 v[50:65], v[70:73], v[78:81], v[50:65]
	s_setprio 0
	ds_read_b128 v[66:69], v104
	ds_read_b128 v[70:73], v104 offset:4096
	ds_read_b128 v[74:77], v108 offset:32768
	ds_read_b128 v[78:81], v108 offset:36864
	s_waitcnt lgkmcnt(4)
	s_setprio 1
	v_mfma_f32_32x32x16_bf16 v[2:17], v[82:85], v[90:93], v[2:17]
	v_mfma_f32_32x32x16_bf16 v[18:33], v[86:89], v[90:93], v[18:33]
	v_mfma_f32_32x32x16_bf16 v[34:49], v[82:85], v[94:97], v[34:49]
	v_mfma_f32_32x32x16_bf16 v[50:65], v[86:89], v[94:97], v[50:65]
	s_setprio 0
	ds_read_b128 v[82:85], v105
	ds_read_b128 v[86:89], v105 offset:4096
	ds_read_b128 v[90:93], v109 offset:32768
	ds_read_b128 v[94:97], v109 offset:36864
	s_waitcnt lgkmcnt(4)
	s_setprio 1
	v_mfma_f32_32x32x16_bf16 v[2:17], v[66:69], v[74:77], v[2:17]
	v_mfma_f32_32x32x16_bf16 v[18:33], v[70:73], v[74:77], v[18:33]
	v_mfma_f32_32x32x16_bf16 v[34:49], v[66:69], v[78:81], v[34:49]
	v_mfma_f32_32x32x16_bf16 v[50:65], v[70:73], v[78:81], v[50:65]
	s_setprio 0
	s_waitcnt lgkmcnt(0)
	s_setprio 1
	v_mfma_f32_32x32x16_bf16 v[2:17], v[82:85], v[90:93], v[2:17]
	v_mfma_f32_32x32x16_bf16 v[18:33], v[86:89], v[90:93], v[18:33]
	v_mfma_f32_32x32x16_bf16 v[34:49], v[82:85], v[94:97], v[34:49]
	v_mfma_f32_32x32x16_bf16 v[50:65], v[86:89], v[94:97], v[50:65]
	s_setprio 0
	s_barrier
	v_readlane_b32 s5, v254, 1
	v_readlane_b32 s8, v254, 4
	v_readlane_b32 s9, v254, 5
	v_readlane_b32 s10, v254, 6
	v_readlane_b32 s11, v254, 7
	v_readlane_b32 s12, v254, 8
	v_readlane_b32 s13, v254, 9
	v_readlane_b32 s14, v254, 10
	v_readlane_b32 s15, v254, 11
	v_readlane_b32 s16, v254, 12
	v_readlane_b32 s17, v254, 13
	v_readlane_b32 s18, v254, 14
	v_readlane_b32 s19, v254, 15
	s_nop 7
	s_barrier
	s_nop 5
	ds_write2_b32 v119, v2, v34 offset1:32
	ds_write2_b32 v119, v3, v35 offset0:65 offset1:97
	ds_write2_b32 v119, v4, v36 offset0:130 offset1:162
	ds_write2_b32 v119, v5, v37 offset0:195 offset1:227
	v_add_u32_e32 v2, 0x800, v119
	ds_write2_b32 v2, v6, v38 offset0:8 offset1:40
	ds_write2_b32 v2, v7, v39 offset0:73 offset1:105
	ds_write2_b32 v2, v8, v40 offset0:138 offset1:170
	ds_write2_b32 v2, v9, v41 offset0:203 offset1:235
	v_add_u32_e32 v2, 0x1000, v119
	ds_write2_b32 v2, v10, v42 offset0:16 offset1:48
	ds_write2_b32 v2, v11, v43 offset0:81 offset1:113
	ds_write2_b32 v2, v12, v44 offset0:146 offset1:178
	ds_write2_b32 v2, v13, v45 offset0:211 offset1:243
	v_add_u32_e32 v2, 0x1800, v119
	ds_write2_b32 v2, v14, v46 offset0:24 offset1:56
	ds_write2_b32 v2, v15, v47 offset0:89 offset1:121
	ds_write2_b32 v2, v16, v48 offset0:154 offset1:186
	ds_write2_b32 v2, v17, v49 offset0:219 offset1:251
	v_add_u32_e32 v2, 0x2000, v119
	ds_write2_b32 v2, v18, v50 offset0:32 offset1:64
	ds_write2_b32 v2, v19, v51 offset0:97 offset1:129
	ds_write2_b32 v2, v20, v52 offset0:162 offset1:194
	v_add_u32_e32 v2, 0x2200, v119
	ds_write2_b32 v2, v21, v53 offset0:99 offset1:131
	v_add_u32_e32 v2, 0x2800, v119
	v_add_u32_e32 v66, s40, v112
	ds_write2_b32 v2, v22, v54 offset0:40 offset1:72
	ds_write2_b32 v2, v23, v55 offset0:105 offset1:137
	ds_write2_b32 v2, v24, v56 offset0:170 offset1:202
	v_add_u32_e32 v2, 0x2a00, v119
	v_ashrrev_i32_e32 v67, 31, v66
	v_readlane_b32 s4, v254, 23
	ds_write2_b32 v2, v25, v57 offset0:107 offset1:139
	v_add_u32_e32 v2, 0x3000, v119
	v_or_b32_e32 v68, s42, v113
	v_lshlrev_b64 v[70:71], 14, v[66:67]
	v_readlane_b32 s6, v254, 25
	v_readlane_b32 s7, v254, 26
	ds_write2_b32 v2, v26, v58 offset0:48 offset1:80
	ds_write2_b32 v2, v27, v59 offset0:113 offset1:145
	ds_write2_b32 v2, v28, v60 offset0:178 offset1:210
	v_add_u32_e32 v2, 0x3200, v119
	v_lshl_add_u64 v[70:71], s[6:7], 0, v[70:71]
	v_ashrrev_i32_e32 v69, 31, v68
	ds_write2_b32 v2, v29, v61 offset0:115 offset1:147
	v_add_u32_e32 v2, 0x3800, v119
	v_lshl_add_u64 v[68:69], v[68:69], 1, v[70:71]
	ds_write2_b32 v2, v30, v62 offset0:56 offset1:88
	ds_write2_b32 v2, v31, v63 offset0:121 offset1:153
	ds_write2_b32 v2, v32, v64 offset0:186 offset1:218
	v_add_u32_e32 v2, 0x3a00, v119
	s_mov_b32 s26, 1
	ds_write2_b32 v2, v33, v65 offset0:123 offset1:155
	v_lshl_add_u64 v[2:3], v[68:69], 0, v[0:1]
	v_lshl_add_u64 v[4:5], v[66:67], 2, s[28:29]
	s_mov_b32 s27, 0
	s_mov_b64 s[0:1], 0
	v_readlane_b32 s5, v254, 24
	s_waitcnt lgkmcnt(0)
	s_barrier

.LBB0_861:
	s_ashr_i32 s0, s49, 31
	s_lshr_b32 s0, s0, 27
	s_add_i32 s0, s49, s0
	s_and_b32 s1, s0, 0xffffe0
	s_sub_i32 s1, s49, s1
	s_lshl_b32 s0, s0, 2
	s_lshl_b32 s20, s1, 8
	s_and_b32 s0, s0, 0xffffff80
	s_ashr_i32 s21, s20, 31
	s_ashr_i32 s1, s0, 31
	v_readlane_b32 s4, v254, 0
	s_lshl_b64 s[22:23], s[20:21], 11
	s_lshl_b64 s[24:25], s[0:1], 11
	v_readlane_b32 s6, v254, 2
	v_readlane_b32 s7, v254, 3
	s_add_u32 s22, s6, s22
	s_addc_u32 s23, s7, s23
	s_add_u32 s24, s50, s24
	s_addc_u32 s25, s51, s25
	s_waitcnt lgkmcnt(0)
	v_lshlrev_b32_e32 v176, 1, v125
	v_lshrrev_b32_e32 v174, 3, v196
	v_lshrrev_b32_e32 v175, 4, v196
	v_xor_b32_e32 v175, v175, v196
	v_and_b32_e32 v175, 7, v175
	v_lshlrev_b32_e32 v175, 4, v175
	v_lshl_or_b32 v162, v174, 11, v175
	v_add_u32_e32 v163, 0x20000, v162
	v_add_u32_e32 v164, 0x40000, v162
	v_add_u32_e32 v165, 0x60000, v162
	v_add_u32_e32 v174, 0, v105
	v_xor_b32_e32 v174, v174, v122
	v_lshlrev_b32_e32 v174, 4, v174
	v_add3_u32 v166, v126, v174, 16
	v_add3_u32 v170, v176, v174, 16
	v_add_u32_e32 v174, 2, v105
	v_xor_b32_e32 v174, v174, v122
	v_lshlrev_b32_e32 v174, 4, v174
	v_add3_u32 v167, v126, v174, 16
	v_add3_u32 v171, v176, v174, 16
	v_add_u32_e32 v174, 4, v105
	v_xor_b32_e32 v174, v174, v122
	v_lshlrev_b32_e32 v174, 4, v174
	v_add3_u32 v168, v126, v174, 16
	v_add3_u32 v172, v176, v174, 16
	v_add_u32_e32 v174, 6, v105
	v_xor_b32_e32 v174, v174, v122
	v_lshlrev_b32_e32 v174, 4, v174
	v_add3_u32 v169, v126, v174, 16
	v_add3_u32 v173, v176, v174, 16
	v_lshrrev_b32_e32 v174, 6, v196
	v_mov_b64_e32 v[16:17], 0
	v_mov_b64_e32 v[18:19], 0
	v_mov_b64_e32 v[20:21], 0
	v_mov_b64_e32 v[22:23], 0
	v_mov_b64_e32 v[24:25], 0
	v_mov_b64_e32 v[26:27], 0
	v_mov_b64_e32 v[28:29], 0
	v_mov_b64_e32 v[30:31], 0
	v_mov_b64_e32 v[32:33], 0
	v_mov_b64_e32 v[34:35], 0
	v_mov_b64_e32 v[36:37], 0
	v_mov_b64_e32 v[38:39], 0
	v_mov_b64_e32 v[40:41], 0
	v_mov_b64_e32 v[42:43], 0
	v_mov_b64_e32 v[44:45], 0
	v_mov_b64_e32 v[46:47], 0
	v_mov_b64_e32 v[48:49], 0
	v_mov_b64_e32 v[50:51], 0
	v_mov_b64_e32 v[52:53], 0
	v_mov_b64_e32 v[54:55], 0
	v_mov_b64_e32 v[56:57], 0
	v_mov_b64_e32 v[58:59], 0
	v_mov_b64_e32 v[60:61], 0
	v_mov_b64_e32 v[62:63], 0
	v_mov_b64_e32 v[64:65], 0
	v_mov_b64_e32 v[66:67], 0
	v_mov_b64_e32 v[68:69], 0
	v_mov_b64_e32 v[70:71], 0
	v_mov_b64_e32 v[72:73], 0
	v_mov_b64_e32 v[74:75], 0
	v_mov_b64_e32 v[76:77], 0
	v_mov_b64_e32 v[78:79], 0
	v_readfirstlane_b32 s27, v174
	s_lshl_b32 s27, s27, 10
	s_add_i32 s27, s27, 16
	s_add_i32 vcc_hi, s27, 0xc000
	s_mov_b32 m0, s27
	s_nop 0
	global_load_lds_dwordx4 v162, s[22:23]
	s_add_u32 m0, m0, 0x2000
	s_nop 0
	global_load_lds_dwordx4 v163, s[22:23]
	s_add_u32 m0, m0, 0x2000
	s_nop 0
	global_load_lds_dwordx4 v164, s[22:23]
	s_add_u32 m0, m0, 0x2000
	s_nop 0
	global_load_lds_dwordx4 v165, s[22:23]
	s_add_u32 m0, m0, 0x2000
	s_nop 0
	global_load_lds_dwordx4 v162, s[24:25]
	s_add_u32 m0, m0, 0x2000
	s_nop 0
	global_load_lds_dwordx4 v163, s[24:25]
	s_add_u32 s22, s22, 0x80
	s_addc_u32 s23, s23, 0
	s_add_u32 s24, s24, 0x80
	s_addc_u32 s25, s25, 0
	s_mov_b32 m0, vcc_hi
	s_nop 0
	global_load_lds_dwordx4 v162, s[22:23]
	s_add_u32 m0, m0, 0x2000
	s_nop 0
	global_load_lds_dwordx4 v163, s[22:23]
	s_add_u32 m0, m0, 0x2000
	s_nop 0
	global_load_lds_dwordx4 v164, s[22:23]
	s_add_u32 m0, m0, 0x2000
	s_nop 0
	global_load_lds_dwordx4 v165, s[22:23]
	s_add_u32 m0, m0, 0x2000
	s_nop 0
	global_load_lds_dwordx4 v162, s[24:25]
	s_add_u32 m0, m0, 0x2000
	s_nop 0
	global_load_lds_dwordx4 v163, s[24:25]
	s_add_u32 s22, s22, 0x80
	s_addc_u32 s23, s23, 0
	s_add_u32 s24, s24, 0x80
	s_addc_u32 s25, s25, 0
	s_mov_b32 s26, 0
	s_movk_i32 s21, 14
	s_waitcnt vmcnt(6)
	s_barrier
	ds_read_b128 v[4:7], v166
	ds_read_b128 v[8:11], v166 offset:4096
	ds_read_b128 v[12:15], v170 offset:32768
	ds_read_b128 v[142:145], v170 offset:36864
.Labin_loop:
	s_add_i32 vcc_hi, s26, 2
	s_cmp_ge_u32 vcc_hi, 3
	s_cselect_b32 vcc_lo, 3, 0
	s_sub_i32 vcc_hi, vcc_hi, vcc_lo
	s_mul_i32 vcc_hi, vcc_hi, 0xc000
	s_add_i32 vcc_hi, vcc_hi, s27
	ds_read_b128 v[146:149], v167
	ds_read_b128 v[150:153], v167 offset:4096
	ds_read_b128 v[154:157], v171 offset:32768
	ds_read_b128 v[158:161], v171 offset:36864
	s_waitcnt lgkmcnt(4)
	s_setprio 1
	v_mfma_f32_32x32x16_bf16 v[32:47], v[4:7], v[12:15], v[32:47]
	s_mov_b32 m0, vcc_hi
	v_mfma_f32_32x32x16_bf16 v[16:31], v[8:11], v[12:15], v[16:31]
	global_load_lds_dwordx4 v162, s[22:23]
	s_add_u32 m0, m0, 0x2000
	v_mfma_f32_32x32x16_bf16 v[48:63], v[4:7], v[142:145], v[48:63]
	global_load_lds_dwordx4 v163, s[22:23]
	s_add_u32 m0, m0, 0x2000
	v_mfma_f32_32x32x16_bf16 v[64:79], v[8:11], v[142:145], v[64:79]
	global_load_lds_dwordx4 v164, s[22:23]
	s_add_u32 m0, m0, 0x2000
	s_nop 0
	global_load_lds_dwordx4 v165, s[22:23]
	s_add_u32 m0, m0, 0x2000
	s_nop 0
	global_load_lds_dwordx4 v162, s[24:25]
	s_add_u32 m0, m0, 0x2000
	s_nop 0
	global_load_lds_dwordx4 v163, s[24:25]
	s_add_u32 s22, s22, 0x80
	s_addc_u32 s23, s23, 0
	s_add_u32 s24, s24, 0x80
	s_addc_u32 s25, s25, 0
	s_setprio 0
	ds_read_b128 v[4:7], v168
	ds_read_b128 v[8:11], v168 offset:4096
	ds_read_b128 v[12:15], v172 offset:32768
	ds_read_b128 v[142:145], v172 offset:36864
	s_waitcnt lgkmcnt(4)
	s_setprio 1
	v_mfma_f32_32x32x16_bf16 v[32:47], v[146:149], v[154:157], v[32:47]
	v_mfma_f32_32x32x16_bf16 v[16:31], v[150:153], v[154:157], v[16:31]
	v_mfma_f32_32x32x16_bf16 v[48:63], v[146:149], v[158:161], v[48:63]
	v_mfma_f32_32x32x16_bf16 v[64:79], v[150:153], v[158:161], v[64:79]
	s_setprio 0
	ds_read_b128 v[146:149], v169
	ds_read_b128 v[150:153], v169 offset:4096
	ds_read_b128 v[154:157], v173 offset:32768
	ds_read_b128 v[158:161], v173 offset:36864
	s_waitcnt lgkmcnt(4)
	s_setprio 1
	v_mfma_f32_32x32x16_bf16 v[32:47], v[4:7], v[12:15], v[32:47]
	v_mfma_f32_32x32x16_bf16 v[16:31], v[8:11], v[12:15], v[16:31]
	v_mfma_f32_32x32x16_bf16 v[48:63], v[4:7], v[142:145], v[48:63]
	v_mfma_f32_32x32x16_bf16 v[64:79], v[8:11], v[142:145], v[64:79]
	s_setprio 0
	s_waitcnt lgkmcnt(0)
	s_waitcnt vmcnt(6)
	s_barrier
	s_add_i32 s26, s26, 1
	s_cmp_eq_u32 s26, 3
	s_cselect_b32 vcc_lo, 0xfffdc000, 0
	s_cselect_b32 s26, 0, s26
	s_add_i32 vcc_lo, vcc_lo, 0xc000
	v_add_u32_e32 v166, vcc_lo, v166
	v_add_u32_e32 v170, vcc_lo, v170
	v_add_u32_e32 v167, vcc_lo, v167
	v_add_u32_e32 v171, vcc_lo, v171
	v_add_u32_e32 v168, vcc_lo, v168
	v_add_u32_e32 v172, vcc_lo, v172
	v_add_u32_e32 v169, vcc_lo, v169
	v_add_u32_e32 v173, vcc_lo, v173
	ds_read_b128 v[4:7], v166
	ds_read_b128 v[8:11], v166 offset:4096
	ds_read_b128 v[12:15], v170 offset:32768
	ds_read_b128 v[142:145], v170 offset:36864
	s_setprio 1
	v_mfma_f32_32x32x16_bf16 v[32:47], v[146:149], v[154:157], v[32:47]
	v_mfma_f32_32x32x16_bf16 v[16:31], v[150:153], v[154:157], v[16:31]
	v_mfma_f32_32x32x16_bf16 v[48:63], v[146:149], v[158:161], v[48:63]
	v_mfma_f32_32x32x16_bf16 v[64:79], v[150:153], v[158:161], v[64:79]
	s_setprio 0
	s_add_i32 s21, s21, -1
	s_cmp_lg_u32 s21, 0
	s_cbranch_scc1 .Labin_loop
	ds_read_b128 v[146:149], v167
	ds_read_b128 v[150:153], v167 offset:4096
	ds_read_b128 v[154:157], v171 offset:32768
	ds_read_b128 v[158:161], v171 offset:36864
	s_waitcnt lgkmcnt(4)
	s_setprio 1
	v_mfma_f32_32x32x16_bf16 v[32:47], v[4:7], v[12:15], v[32:47]
	v_mfma_f32_32x32x16_bf16 v[16:31], v[8:11], v[12:15], v[16:31]
	v_mfma_f32_32x32x16_bf16 v[48:63], v[4:7], v[142:145], v[48:63]
	v_mfma_f32_32x32x16_bf16 v[64:79], v[8:11], v[142:145], v[64:79]
	s_setprio 0
	ds_read_b128 v[4:7], v168
	ds_read_b128 v[8:11], v168 offset:4096
	ds_read_b128 v[12:15], v172 offset:32768
	ds_read_b128 v[142:145], v172 offset:36864
	s_waitcnt lgkmcnt(4)
	s_setprio 1
	v_mfma_f32_32x32x16_bf16 v[32:47], v[146:149], v[154:157], v[32:47]
	v_mfma_f32_32x32x16_bf16 v[16:31], v[150:153], v[154:157], v[16:31]
	v_mfma_f32_32x32x16_bf16 v[48:63], v[146:149], v[158:161], v[48:63]
	v_mfma_f32_32x32x16_bf16 v[64:79], v[150:153], v[158:161], v[64:79]
	s_setprio 0
	ds_read_b128 v[146:149], v169
	ds_read_b128 v[150:153], v169 offset:4096
	ds_read_b128 v[154:157], v173 offset:32768
	ds_read_b128 v[158:161], v173 offset:36864
	s_waitcnt lgkmcnt(4)
	s_setprio 1
	v_mfma_f32_32x32x16_bf16 v[32:47], v[4:7], v[12:15], v[32:47]
	v_mfma_f32_32x32x16_bf16 v[16:31], v[8:11], v[12:15], v[16:31]
	v_mfma_f32_32x32x16_bf16 v[48:63], v[4:7], v[142:145], v[48:63]
	v_mfma_f32_32x32x16_bf16 v[64:79], v[8:11], v[142:145], v[64:79]
	s_setprio 0
	s_waitcnt lgkmcnt(0)
	s_waitcnt vmcnt(0)
	s_barrier
	s_add_i32 s26, s26, 1
	s_cmp_eq_u32 s26, 3
	s_cselect_b32 vcc_lo, 0xfffdc000, 0
	s_cselect_b32 s26, 0, s26
	s_add_i32 vcc_lo, vcc_lo, 0xc000
	v_add_u32_e32 v166, vcc_lo, v166
	v_add_u32_e32 v170, vcc_lo, v170
	v_add_u32_e32 v167, vcc_lo, v167
	v_add_u32_e32 v171, vcc_lo, v171
	v_add_u32_e32 v168, vcc_lo, v168
	v_add_u32_e32 v172, vcc_lo, v172
	v_add_u32_e32 v169, vcc_lo, v169
	v_add_u32_e32 v173, vcc_lo, v173
	ds_read_b128 v[4:7], v166
	ds_read_b128 v[8:11], v166 offset:4096
	ds_read_b128 v[12:15], v170 offset:32768
	ds_read_b128 v[142:145], v170 offset:36864
	s_setprio 1
	v_mfma_f32_32x32x16_bf16 v[32:47], v[146:149], v[154:157], v[32:47]
	v_mfma_f32_32x32x16_bf16 v[16:31], v[150:153], v[154:157], v[16:31]
	v_mfma_f32_32x32x16_bf16 v[48:63], v[146:149], v[158:161], v[48:63]
	v_mfma_f32_32x32x16_bf16 v[64:79], v[150:153], v[158:161], v[64:79]
	s_setprio 0
	ds_read_b128 v[146:149], v167
	ds_read_b128 v[150:153], v167 offset:4096
	ds_read_b128 v[154:157], v171 offset:32768
	ds_read_b128 v[158:161], v171 offset:36864
	s_waitcnt lgkmcnt(4)
	s_setprio 1
	v_mfma_f32_32x32x16_bf16 v[32:47], v[4:7], v[12:15], v[32:47]
	v_mfma_f32_32x32x16_bf16 v[16:31], v[8:11], v[12:15], v[16:31]
	v_mfma_f32_32x32x16_bf16 v[48:63], v[4:7], v[142:145], v[48:63]
	v_mfma_f32_32x32x16_bf16 v[64:79], v[8:11], v[142:145], v[64:79]
	s_setprio 0
	ds_read_b128 v[4:7], v168
	ds_read_b128 v[8:11], v168 offset:4096
	ds_read_b128 v[12:15], v172 offset:32768
	ds_read_b128 v[142:145], v172 offset:36864
	s_waitcnt lgkmcnt(4)
	s_setprio 1
	v_mfma_f32_32x32x16_bf16 v[32:47], v[146:149], v[154:157], v[32:47]
	v_mfma_f32_32x32x16_bf16 v[16:31], v[150:153], v[154:157], v[16:31]
	v_mfma_f32_32x32x16_bf16 v[48:63], v[146:149], v[158:161], v[48:63]
	v_mfma_f32_32x32x16_bf16 v[64:79], v[150:153], v[158:161], v[64:79]
	s_setprio 0
	ds_read_b128 v[146:149], v169
	ds_read_b128 v[150:153], v169 offset:4096
	ds_read_b128 v[154:157], v173 offset:32768
	ds_read_b128 v[158:161], v173 offset:36864
	s_waitcnt lgkmcnt(4)
	s_setprio 1
	v_mfma_f32_32x32x16_bf16 v[32:47], v[4:7], v[12:15], v[32:47]
	v_mfma_f32_32x32x16_bf16 v[16:31], v[8:11], v[12:15], v[16:31]
	v_mfma_f32_32x32x16_bf16 v[48:63], v[4:7], v[142:145], v[48:63]
	v_mfma_f32_32x32x16_bf16 v[64:79], v[8:11], v[142:145], v[64:79]
	s_setprio 0
	s_waitcnt lgkmcnt(0)
	s_setprio 1
	v_mfma_f32_32x32x16_bf16 v[32:47], v[146:149], v[154:157], v[32:47]
	v_mfma_f32_32x32x16_bf16 v[16:31], v[150:153], v[154:157], v[16:31]
	v_mfma_f32_32x32x16_bf16 v[48:63], v[146:149], v[158:161], v[48:63]
	v_mfma_f32_32x32x16_bf16 v[64:79], v[150:153], v[158:161], v[64:79]
	s_setprio 0
	s_barrier
	v_mov_b32_e32 v0, v1
	v_readlane_b32 s4, v254, 0
	v_readlane_b32 s5, v254, 1
	v_readlane_b32 s6, v254, 2
	v_readlane_b32 s7, v254, 3
	v_readlane_b32 s8, v254, 4
	v_readlane_b32 s9, v254, 5
	v_readlane_b32 s10, v254, 6
	v_readlane_b32 s11, v254, 7
	v_readlane_b32 s12, v254, 8
	v_readlane_b32 s13, v254, 9
	v_readlane_b32 s14, v254, 10
	v_readlane_b32 s15, v254, 11
	v_readlane_b32 s16, v254, 12
	v_readlane_b32 s17, v254, 13
	v_readlane_b32 s18, v254, 14
	v_readlane_b32 s19, v254, 15
	s_nop 7
	v_add_u32_e32 v2, s20, v123
	s_movk_i32 s1, 0x1000
	v_cmp_gt_i32_e64 s[42:43], s1, v2
	v_add_u32_e32 v3, 0xfffff000, v2
	s_movk_i32 s1, 0xfff
	v_lshrrev_b32_e32 v3, 11, v3
	v_ashrrev_i32_e32 v10, 8, v2
	v_cmp_lt_i32_e64 s[44:45], s1, v2
	ds_write2_b32 v141, v32, v48 offset1:32
	ds_write2_b32 v141, v33, v49 offset0:65 offset1:97
	ds_write2_b32 v141, v34, v50 offset0:130 offset1:162
	ds_write2_b32 v141, v35, v51 offset0:195 offset1:227
	v_cndmask_b32_e64 v9, v10, v3, s[44:45]
	v_and_b32_e32 v3, 0x7c0, v2
	v_cndmask_b32_e64 v8, v127, v3, s[44:45]
	v_add_u32_e32 v3, 0x800, v141
	ds_write2_b32 v3, v36, v52 offset0:8 offset1:40
	ds_write2_b32 v3, v37, v53 offset0:73 offset1:105
	ds_write2_b32 v3, v38, v54 offset0:138 offset1:170
	ds_write2_b32 v3, v39, v55 offset0:203 offset1:235
	v_add_u32_e32 v3, 0x1000, v141
	ds_write2_b32 v3, v40, v56 offset0:16 offset1:48
	ds_write2_b32 v3, v41, v57 offset0:81 offset1:113
	ds_write2_b32 v3, v42, v58 offset0:146 offset1:178
	ds_write2_b32 v3, v43, v59 offset0:211 offset1:243
	v_add_u32_e32 v3, 0x1800, v141
	ds_write2_b32 v3, v44, v60 offset0:24 offset1:56
	ds_write2_b32 v3, v45, v61 offset0:89 offset1:121
	ds_write2_b32 v3, v46, v62 offset0:154 offset1:186
	ds_write2_b32 v3, v47, v63 offset0:219 offset1:251
	v_add_u32_e32 v3, 0x2000, v141
	ds_write2_b32 v3, v16, v64 offset0:32 offset1:64
	ds_write2_b32 v3, v17, v65 offset0:97 offset1:129
	ds_write2_b32 v3, v18, v66 offset0:162 offset1:194
	v_add_u32_e32 v3, 0x2200, v141
	ds_write2_b32 v3, v19, v67 offset0:99 offset1:131
	v_add_u32_e32 v3, 0x2800, v141
	ds_write2_b32 v3, v20, v68 offset0:40 offset1:72
	ds_write2_b32 v3, v21, v69 offset0:105 offset1:137
	ds_write2_b32 v3, v22, v70 offset0:170 offset1:202
	v_add_u32_e32 v3, 0x2a00, v141
	ds_write2_b32 v3, v23, v71 offset0:107 offset1:139
	v_add_u32_e32 v3, 0x3000, v141
	ds_write2_b32 v3, v24, v72 offset0:48 offset1:80
	ds_write2_b32 v3, v25, v73 offset0:113 offset1:145
	ds_write2_b32 v3, v26, v74 offset0:178 offset1:210
	v_add_u32_e32 v3, 0x3200, v141
	v_or_b32_e32 v0, s0, v124
	s_movk_i32 s1, 0x3ff
	ds_write2_b32 v3, v27, v75 offset0:115 offset1:147
	v_add_u32_e32 v3, 0x3800, v141
	v_cmp_lt_i32_e32 vcc, s1, v0
	ds_write2_b32 v3, v28, v76 offset0:56 offset1:88
	ds_write2_b32 v3, v29, v77 offset0:121 offset1:153
	ds_write2_b32 v3, v30, v78 offset0:186 offset1:218
	v_add_u32_e32 v3, 0x3a00, v141
	ds_write2_b32 v3, v31, v79 offset0:123 offset1:155
	s_waitcnt lgkmcnt(0)
	s_barrier
	s_and_saveexec_b64 s[20:21], vcc
	s_xor_b64 s[28:29], exec, s[20:21]
	s_cbranch_execz .LBB0_880
	s_cmpk_gt_u32 s0, 0x5ff
	s_mov_b64 s[0:1], -1
	s_cbranch_scc0 .LBB0_873
	v_readlane_b32 s4, v253, 46
	v_readlane_b32 s12, v253, 54
	v_readlane_b32 s13, v253, 55
	s_movk_i32 s0, 0x1c00
	s_mov_b32 s20, 1
	v_mov_b64_e32 v[4:5], s[12:13]
	v_mad_i64_i32 v[2:3], s[0:1], v2, s0, v[4:5]
	v_lshl_add_u64 v[2:3], v[0:1], 2, v[2:3]
	v_lshlrev_b32_e32 v4, 2, v104
	v_mov_b32_e32 v5, v1
	s_movk_i32 s0, 0xe800
	v_lshl_add_u64 v[2:3], v[2:3], 0, v[4:5]
	s_mov_b32 s1, -1
	v_lshl_add_u64 v[2:3], v[2:3], 0, s[0:1]
	s_mov_b32 s21, 0
	s_mov_b32 s22, 64
	v_readlane_b32 s5, v253, 47
	v_readlane_b32 s6, v253, 48
	v_readlane_b32 s7, v253, 49
	v_readlane_b32 s8, v253, 50
	v_readlane_b32 s9, v253, 51
	v_readlane_b32 s10, v253, 52
	v_readlane_b32 s11, v253, 53
	v_readlane_b32 s14, v253, 56
	v_readlane_b32 s15, v253, 57
	v_readlane_b32 s16, v253, 58
	v_readlane_b32 s17, v253, 59
	v_readlane_b32 s18, v253, 60
	v_readlane_b32 s19, v253, 61

.LBB0_954:
	s_ashr_i32 s0, s23, 31
	s_lshr_b32 s0, s0, 27
	s_add_i32 s20, s23, s0
	s_and_b32 s0, s20, 0xffffffe0
	s_sub_i32 s26, s23, s0
	s_mul_i32 s0, s26, 0xb0000
	s_ashr_i32 s1, s0, 31
	s_lshl_b32 s20, s20, 2
	s_and_b32 s27, s20, 0xffffff80
	s_lshl_b64 s[0:1], s[0:1], 1
	v_readlane_b32 s4, v254, 21
	v_readlane_b32 s5, v254, 22
	s_add_u32 s0, s4, s0
	s_addc_u32 s1, s5, s1
	s_mul_i32 s20, s27, 0x1600
	s_mul_hi_i32 s21, s27, 0x1600
	s_add_u32 s20, s24, s20
	s_addc_u32 s21, s25, s21
	s_waitcnt lgkmcnt(0)
	v_lshlrev_b32_e32 v142, 1, v133
	v_lshrrev_b32_e32 v140, 3, v196
	v_lshrrev_b32_e32 v141, 4, v196
	v_xor_b32_e32 v141, v141, v196
	v_and_b32_e32 v141, 7, v141
	v_lshlrev_b32_e32 v141, 4, v141
	v_mul_u32_u24_e32 v140, 0x1600, v140
	v_add_u32_e32 v82, v140, v141
	v_add_u32_e32 v83, 0x58000, v82
	v_add_u32_e32 v84, 0xb0000, v82
	v_add_u32_e32 v85, 0x108000, v82
	v_add_u32_e32 v140, 0, v130
	v_xor_b32_e32 v140, v140, v131
	v_lshlrev_b32_e32 v140, 4, v140
	v_add3_u32 v86, v134, v140, 16
	v_add3_u32 v136, v142, v140, 16
	v_add_u32_e32 v140, 2, v130
	v_xor_b32_e32 v140, v140, v131
	v_lshlrev_b32_e32 v140, 4, v140
	v_add3_u32 v87, v134, v140, 16
	v_add3_u32 v137, v142, v140, 16
	v_add_u32_e32 v140, 4, v130
	v_xor_b32_e32 v140, v140, v131
	v_lshlrev_b32_e32 v140, 4, v140
	v_add3_u32 v88, v134, v140, 16
	v_add3_u32 v138, v142, v140, 16
	v_add_u32_e32 v140, 6, v130
	v_xor_b32_e32 v140, v140, v131
	v_lshlrev_b32_e32 v140, 4, v140
	v_add3_u32 v89, v134, v140, 16
	v_add3_u32 v139, v142, v140, 16
	v_lshrrev_b32_e32 v140, 6, v196
	v_mov_b64_e32 v[2:3], 0
	v_mov_b64_e32 v[4:5], 0
	v_mov_b64_e32 v[6:7], 0
	v_mov_b64_e32 v[8:9], 0
	v_mov_b64_e32 v[10:11], 0
	v_mov_b64_e32 v[12:13], 0
	v_mov_b64_e32 v[14:15], 0
	v_mov_b64_e32 v[16:17], 0
	v_mov_b64_e32 v[18:19], 0
	v_mov_b64_e32 v[20:21], 0
	v_mov_b64_e32 v[22:23], 0
	v_mov_b64_e32 v[24:25], 0
	v_mov_b64_e32 v[26:27], 0
	v_mov_b64_e32 v[28:29], 0
	v_mov_b64_e32 v[30:31], 0
	v_mov_b64_e32 v[32:33], 0
	v_mov_b64_e32 v[34:35], 0
	v_mov_b64_e32 v[36:37], 0
	v_mov_b64_e32 v[38:39], 0
	v_mov_b64_e32 v[40:41], 0
	v_mov_b64_e32 v[42:43], 0
	v_mov_b64_e32 v[44:45], 0
	v_mov_b64_e32 v[46:47], 0
	v_mov_b64_e32 v[48:49], 0
	v_mov_b64_e32 v[50:51], 0
	v_mov_b64_e32 v[52:53], 0
	v_mov_b64_e32 v[54:55], 0
	v_mov_b64_e32 v[56:57], 0
	v_mov_b64_e32 v[58:59], 0
	v_mov_b64_e32 v[60:61], 0
	v_mov_b64_e32 v[62:63], 0
	v_mov_b64_e32 v[64:65], 0
	v_readfirstlane_b32 s43, v140
	s_lshl_b32 s43, s43, 10
	s_add_i32 s43, s43, 16
	s_add_i32 vcc_hi, s43, 0xc000
	s_mov_b32 m0, s43
	s_nop 0
	global_load_lds_dwordx4 v82, s[0:1]
	s_add_u32 m0, m0, 0x2000
	s_nop 0
	global_load_lds_dwordx4 v83, s[0:1]
	s_add_u32 m0, m0, 0x2000
	s_nop 0
	global_load_lds_dwordx4 v84, s[0:1]
	s_add_u32 m0, m0, 0x2000
	s_nop 0
	global_load_lds_dwordx4 v85, s[0:1]
	s_add_u32 m0, m0, 0x2000
	s_nop 0
	global_load_lds_dwordx4 v82, s[20:21]
	s_add_u32 m0, m0, 0x2000
	s_nop 0
	global_load_lds_dwordx4 v83, s[20:21]
	s_add_u32 s0, s0, 0x80
	s_addc_u32 s1, s1, 0
	s_add_u32 s20, s20, 0x80
	s_addc_u32 s21, s21, 0
	s_mov_b32 m0, vcc_hi
	s_nop 0
	global_load_lds_dwordx4 v82, s[0:1]
	s_add_u32 m0, m0, 0x2000
	s_nop 0
	global_load_lds_dwordx4 v83, s[0:1]
	s_add_u32 m0, m0, 0x2000
	s_nop 0
	global_load_lds_dwordx4 v84, s[0:1]
	s_add_u32 m0, m0, 0x2000
	s_nop 0
	global_load_lds_dwordx4 v85, s[0:1]
	s_add_u32 m0, m0, 0x2000
	s_nop 0
	global_load_lds_dwordx4 v82, s[20:21]
	s_add_u32 m0, m0, 0x2000
	s_nop 0
	global_load_lds_dwordx4 v83, s[20:21]
	s_add_u32 s0, s0, 0x80
	s_addc_u32 s1, s1, 0
	s_add_u32 s20, s20, 0x80
	s_addc_u32 s21, s21, 0
	s_mov_b32 s41, 0
	s_movk_i32 s40, 42
	s_waitcnt vmcnt(6)
	s_barrier
	ds_read_b128 v[144:147], v86
	ds_read_b128 v[148:151], v86 offset:4096
	ds_read_b128 v[152:155], v136 offset:32768
	ds_read_b128 v[156:159], v136 offset:36864
.Lw2_loop:
	s_add_i32 vcc_hi, s41, 2
	s_cmp_ge_u32 vcc_hi, 3
	s_cselect_b32 vcc_lo, 3, 0
	s_sub_i32 vcc_hi, vcc_hi, vcc_lo
	s_mul_i32 vcc_hi, vcc_hi, 0xc000
	s_add_i32 vcc_hi, vcc_hi, s43
	ds_read_b128 v[66:69], v87
	ds_read_b128 v[70:73], v87 offset:4096
	ds_read_b128 v[74:77], v137 offset:32768
	ds_read_b128 v[78:81], v137 offset:36864
	s_waitcnt lgkmcnt(4)
	s_setprio 1
	v_mfma_f32_32x32x16_bf16 v[50:65], v[144:147], v[152:155], v[50:65]
	s_mov_b32 m0, vcc_hi
	v_mfma_f32_32x32x16_bf16 v[18:33], v[148:151], v[152:155], v[18:33]
	global_load_lds_dwordx4 v82, s[0:1]
	s_add_u32 m0, m0, 0x2000
	v_mfma_f32_32x32x16_bf16 v[34:49], v[144:147], v[156:159], v[34:49]
	global_load_lds_dwordx4 v83, s[0:1]
	s_add_u32 m0, m0, 0x2000
	v_mfma_f32_32x32x16_bf16 v[2:17], v[148:151], v[156:159], v[2:17]
	global_load_lds_dwordx4 v84, s[0:1]
	s_add_u32 m0, m0, 0x2000
	s_nop 0
	global_load_lds_dwordx4 v85, s[0:1]
	s_add_u32 m0, m0, 0x2000
	s_nop 0
	global_load_lds_dwordx4 v82, s[20:21]
	s_add_u32 m0, m0, 0x2000
	s_nop 0
	global_load_lds_dwordx4 v83, s[20:21]
	s_add_u32 s0, s0, 0x80
	s_addc_u32 s1, s1, 0
	s_add_u32 s20, s20, 0x80
	s_addc_u32 s21, s21, 0
	s_setprio 0
	ds_read_b128 v[144:147], v88
	ds_read_b128 v[148:151], v88 offset:4096
	ds_read_b128 v[152:155], v138 offset:32768
	ds_read_b128 v[156:159], v138 offset:36864
	s_waitcnt lgkmcnt(4)
	s_setprio 1
	v_mfma_f32_32x32x16_bf16 v[50:65], v[66:69], v[74:77], v[50:65]
	v_mfma_f32_32x32x16_bf16 v[18:33], v[70:73], v[74:77], v[18:33]
	v_mfma_f32_32x32x16_bf16 v[34:49], v[66:69], v[78:81], v[34:49]
	v_mfma_f32_32x32x16_bf16 v[2:17], v[70:73], v[78:81], v[2:17]
	s_setprio 0
	ds_read_b128 v[66:69], v89
	ds_read_b128 v[70:73], v89 offset:4096
	ds_read_b128 v[74:77], v139 offset:32768
	ds_read_b128 v[78:81], v139 offset:36864
	s_waitcnt lgkmcnt(4)
	s_setprio 1
	v_mfma_f32_32x32x16_bf16 v[50:65], v[144:147], v[152:155], v[50:65]
	v_mfma_f32_32x32x16_bf16 v[18:33], v[148:151], v[152:155], v[18:33]
	v_mfma_f32_32x32x16_bf16 v[34:49], v[144:147], v[156:159], v[34:49]
	v_mfma_f32_32x32x16_bf16 v[2:17], v[148:151], v[156:159], v[2:17]
	s_setprio 0
	s_waitcnt lgkmcnt(0)
	s_waitcnt vmcnt(6)
	s_barrier
	s_add_i32 s41, s41, 1
	s_cmp_eq_u32 s41, 3
	s_cselect_b32 vcc_lo, 0xfffdc000, 0
	s_cselect_b32 s41, 0, s41
	s_add_i32 vcc_lo, vcc_lo, 0xc000
	v_add_u32_e32 v86, vcc_lo, v86
	v_add_u32_e32 v136, vcc_lo, v136
	v_add_u32_e32 v87, vcc_lo, v87
	v_add_u32_e32 v137, vcc_lo, v137
	v_add_u32_e32 v88, vcc_lo, v88
	v_add_u32_e32 v138, vcc_lo, v138
	v_add_u32_e32 v89, vcc_lo, v89
	v_add_u32_e32 v139, vcc_lo, v139
	ds_read_b128 v[144:147], v86
	ds_read_b128 v[148:151], v86 offset:4096
	ds_read_b128 v[152:155], v136 offset:32768
	ds_read_b128 v[156:159], v136 offset:36864
	s_setprio 1
	v_mfma_f32_32x32x16_bf16 v[50:65], v[66:69], v[74:77], v[50:65]
	v_mfma_f32_32x32x16_bf16 v[18:33], v[70:73], v[74:77], v[18:33]
	v_mfma_f32_32x32x16_bf16 v[34:49], v[66:69], v[78:81], v[34:49]
	v_mfma_f32_32x32x16_bf16 v[2:17], v[70:73], v[78:81], v[2:17]
	s_setprio 0
	s_add_i32 s40, s40, -1
	s_cmp_lg_u32 s40, 0
	s_cbranch_scc1 .Lw2_loop
	ds_read_b128 v[66:69], v87
	ds_read_b128 v[70:73], v87 offset:4096
	ds_read_b128 v[74:77], v137 offset:32768
	ds_read_b128 v[78:81], v137 offset:36864
	s_waitcnt lgkmcnt(4)
	s_setprio 1
	v_mfma_f32_32x32x16_bf16 v[50:65], v[144:147], v[152:155], v[50:65]
	v_mfma_f32_32x32x16_bf16 v[18:33], v[148:151], v[152:155], v[18:33]
	v_mfma_f32_32x32x16_bf16 v[34:49], v[144:147], v[156:159], v[34:49]
	v_mfma_f32_32x32x16_bf16 v[2:17], v[148:151], v[156:159], v[2:17]
	s_setprio 0
	ds_read_b128 v[144:147], v88
	ds_read_b128 v[148:151], v88 offset:4096
	ds_read_b128 v[152:155], v138 offset:32768
	ds_read_b128 v[156:159], v138 offset:36864
	s_waitcnt lgkmcnt(4)
	s_setprio 1
	v_mfma_f32_32x32x16_bf16 v[50:65], v[66:69], v[74:77], v[50:65]
	v_mfma_f32_32x32x16_bf16 v[18:33], v[70:73], v[74:77], v[18:33]
	v_mfma_f32_32x32x16_bf16 v[34:49], v[66:69], v[78:81], v[34:49]
	v_mfma_f32_32x32x16_bf16 v[2:17], v[70:73], v[78:81], v[2:17]
	s_setprio 0
	ds_read_b128 v[66:69], v89
	ds_read_b128 v[70:73], v89 offset:4096
	ds_read_b128 v[74:77], v139 offset:32768
	ds_read_b128 v[78:81], v139 offset:36864
	s_waitcnt lgkmcnt(4)
	s_setprio 1
	v_mfma_f32_32x32x16_bf16 v[50:65], v[144:147], v[152:155], v[50:65]
	v_mfma_f32_32x32x16_bf16 v[18:33], v[148:151], v[152:155], v[18:33]
	v_mfma_f32_32x32x16_bf16 v[34:49], v[144:147], v[156:159], v[34:49]
	v_mfma_f32_32x32x16_bf16 v[2:17], v[148:151], v[156:159], v[2:17]
	s_setprio 0
	s_waitcnt lgkmcnt(0)
	s_waitcnt vmcnt(0)
	s_barrier
	s_add_i32 s41, s41, 1
	s_cmp_eq_u32 s41, 3
	s_cselect_b32 vcc_lo, 0xfffdc000, 0
	s_cselect_b32 s41, 0, s41
	s_add_i32 vcc_lo, vcc_lo, 0xc000
	v_add_u32_e32 v86, vcc_lo, v86
	v_add_u32_e32 v136, vcc_lo, v136
	v_add_u32_e32 v87, vcc_lo, v87
	v_add_u32_e32 v137, vcc_lo, v137
	v_add_u32_e32 v88, vcc_lo, v88
	v_add_u32_e32 v138, vcc_lo, v138
	v_add_u32_e32 v89, vcc_lo, v89
	v_add_u32_e32 v139, vcc_lo, v139
	ds_read_b128 v[144:147], v86
	ds_read_b128 v[148:151], v86 offset:4096
	ds_read_b128 v[152:155], v136 offset:32768
	ds_read_b128 v[156:159], v136 offset:36864
	s_setprio 1
	v_mfma_f32_32x32x16_bf16 v[50:65], v[66:69], v[74:77], v[50:65]
	v_mfma_f32_32x32x16_bf16 v[18:33], v[70:73], v[74:77], v[18:33]
	v_mfma_f32_32x32x16_bf16 v[34:49], v[66:69], v[78:81], v[34:49]
	v_mfma_f32_32x32x16_bf16 v[2:17], v[70:73], v[78:81], v[2:17]
	s_setprio 0
	ds_read_b128 v[66:69], v87
	ds_read_b128 v[70:73], v87 offset:4096
	ds_read_b128 v[74:77], v137 offset:32768
	ds_read_b128 v[78:81], v137 offset:36864
	s_waitcnt lgkmcnt(4)
	s_setprio 1
	v_mfma_f32_32x32x16_bf16 v[50:65], v[144:147], v[152:155], v[50:65]
	v_mfma_f32_32x32x16_bf16 v[18:33], v[148:151], v[152:155], v[18:33]
	v_mfma_f32_32x32x16_bf16 v[34:49], v[144:147], v[156:159], v[34:49]
	v_mfma_f32_32x32x16_bf16 v[2:17], v[148:151], v[156:159], v[2:17]
	s_setprio 0
	ds_read_b128 v[144:147], v88
	ds_read_b128 v[148:151], v88 offset:4096
	ds_read_b128 v[152:155], v138 offset:32768
	ds_read_b128 v[156:159], v138 offset:36864
	s_waitcnt lgkmcnt(4)
	s_setprio 1
	v_mfma_f32_32x32x16_bf16 v[50:65], v[66:69], v[74:77], v[50:65]
	v_mfma_f32_32x32x16_bf16 v[18:33], v[70:73], v[74:77], v[18:33]
	v_mfma_f32_32x32x16_bf16 v[34:49], v[66:69], v[78:81], v[34:49]
	v_mfma_f32_32x32x16_bf16 v[2:17], v[70:73], v[78:81], v[2:17]
	s_setprio 0
	ds_read_b128 v[66:69], v89
	ds_read_b128 v[70:73], v89 offset:4096
	ds_read_b128 v[74:77], v139 offset:32768
	ds_read_b128 v[78:81], v139 offset:36864
	s_waitcnt lgkmcnt(4)
	s_setprio 1
	v_mfma_f32_32x32x16_bf16 v[50:65], v[144:147], v[152:155], v[50:65]
	v_mfma_f32_32x32x16_bf16 v[18:33], v[148:151], v[152:155], v[18:33]
	v_mfma_f32_32x32x16_bf16 v[34:49], v[144:147], v[156:159], v[34:49]
	v_mfma_f32_32x32x16_bf16 v[2:17], v[148:151], v[156:159], v[2:17]
	s_setprio 0
	s_waitcnt lgkmcnt(0)
	s_setprio 1
	v_mfma_f32_32x32x16_bf16 v[50:65], v[66:69], v[74:77], v[50:65]
	v_mfma_f32_32x32x16_bf16 v[18:33], v[70:73], v[74:77], v[18:33]
	v_mfma_f32_32x32x16_bf16 v[34:49], v[66:69], v[78:81], v[34:49]
	v_mfma_f32_32x32x16_bf16 v[2:17], v[70:73], v[78:81], v[2:17]
	s_setprio 0
	s_barrier
	v_mov_b32_e32 v0, v1
	s_nop 7
	s_waitcnt vmcnt(5)
	v_lshl_add_u32 v68, s26, 8, v132
	v_add_u32_e32 v0, 0xfffff000, v68
	v_lshrrev_b32_e32 v0, 11, v0
	s_movk_i32 s0, 0x1800
	v_mad_u32_u24 v0, v0, s0, s0
	v_cmp_lt_i32_e32 vcc, s50, v68
	v_ashrrev_i32_e32 v69, 31, v68
	v_readlane_b32 s4, v254, 0
	v_or_b32_e32 v66, s27, v135
	v_cndmask_b32_e32 v160, 0, v0, vcc
	s_waitcnt vmcnt(4)
	v_lshlrev_b64 v[70:71], 12, v[68:69]
	v_readlane_b32 s5, v254, 1
	v_ashrrev_i32_e32 v67, 31, v66
	v_mov_b32_e32 v95, v1
	v_lshl_add_u64 v[72:73], s[4:5], 0, v[70:71]
	v_add_u32_e32 v70, v160, v66
	v_ashrrev_i32_e32 v71, 31, v70
	v_lshl_add_u64 v[70:71], v[70:71], 2, s[28:29]
	global_load_dword v69, v[70:71], off
	v_lshlrev_b64 v[70:71], 2, v[66:67]
	s_waitcnt vmcnt(4)
	v_lshl_add_u64 v[74:75], v[72:73], 0, v[70:71]
	v_mov_b32_e32 v109, v1
	v_mov_b32_e32 v111, v1
	v_lshl_add_u64 v[72:73], v[74:75], 0, v[94:95]
	v_mov_b32_e32 v97, v1
	v_mov_b32_e32 v99, v1
	v_mov_b32_e32 v101, v1
	v_mov_b32_e32 v103, v1
	v_mov_b32_e32 v105, v1
	v_mov_b32_e32 v107, v1
	s_waitcnt vmcnt(1)
	v_lshl_add_u64 v[88:89], v[74:75], 0, v[108:109]
	v_lshl_add_u64 v[144:145], v[74:75], 0, v[110:111]
	v_mov_b32_e32 v113, v1
	v_lshl_add_u64 v[76:77], v[74:75], 0, v[96:97]
	v_lshl_add_u64 v[78:79], v[74:75], 0, v[98:99]
	v_lshl_add_u64 v[80:81], v[74:75], 0, v[100:101]
	v_lshl_add_u64 v[82:83], v[74:75], 0, v[102:103]
	v_lshl_add_u64 v[84:85], v[74:75], 0, v[104:105]
	v_lshl_add_u64 v[86:87], v[74:75], 0, v[106:107]
	global_load_dword v67, v[72:73], off
	global_load_dword v161, v[76:77], off
	global_load_dword v162, v[78:79], off
	global_load_dword v163, v[80:81], off
	global_load_dword v164, v[82:83], off
	global_load_dword v165, v[84:85], off
	global_load_dword v166, v[86:87], off
	global_load_dword v167, v[88:89], off
	global_load_dword v168, v[144:145], off
	v_lshl_add_u64 v[146:147], v[74:75], 0, v[112:113]
	v_mov_b32_e32 v115, v1
	global_load_dword v169, v[146:147], off
	v_lshl_add_u64 v[148:149], v[74:75], 0, v[114:115]
	v_mov_b32_e32 v117, v1
	global_load_dword v170, v[148:149], off
	v_lshl_add_u64 v[150:151], v[74:75], 0, v[116:117]
	v_mov_b32_e32 v119, v1
	global_load_dword v171, v[150:151], off
	v_lshl_add_u64 v[152:153], v[74:75], 0, v[118:119]
	v_mov_b32_e32 v121, v1
	global_load_dword v172, v[152:153], off
	v_lshl_add_u64 v[154:155], v[74:75], 0, v[120:121]
	v_mov_b32_e32 v123, v1
	global_load_dword v173, v[154:155], off
	global_load_dword v177, v[72:73], off offset:128
	v_lshl_add_u64 v[156:157], v[74:75], 0, v[122:123]
	v_mov_b32_e32 v125, v1
	global_load_dword v174, v[156:157], off
	v_lshl_add_u64 v[158:159], v[74:75], 0, v[124:125]
	global_load_dword v175, v[158:159], off
	v_add_f32_e32 v50, 0, v50
	v_add_f32_e32 v51, 0, v51
	v_add_f32_e32 v52, 0, v52
	v_add_f32_e32 v53, 0, v53
	v_add_f32_e32 v54, 0, v54
	v_add_f32_e32 v55, 0, v55
	v_add_f32_e32 v56, 0, v56
	v_add_f32_e32 v57, 0, v57
	v_or_b32_e32 v176, 32, v66
	s_mov_b64 s[0:1], 0x80
	v_add_f32_e32 v34, 0, v34
	v_add_f32_e32 v35, 0, v35
	v_add_f32_e32 v36, 0, v36
	v_add_f32_e32 v37, 0, v37
	v_add_f32_e32 v41, 0, v41
	v_add_f32_e32 v38, 0, v38
	v_add_f32_e32 v39, 0, v39
	v_add_f32_e32 v40, 0, v40
	v_add_f32_e32 v18, 0, v18
	v_add_f32_e32 v19, 0, v19
	v_add_f32_e32 v20, 0, v20
	v_add_f32_e32 v21, 0, v21
	v_add_f32_e32 v2, 0, v2
	s_add_i32 s23, s23, s22
	v_add_f32_e32 v3, 0, v3
	v_add_f32_e32 v4, 0, v4
	v_add_f32_e32 v5, 0, v5
	s_cmpk_gt_i32 s23, 0xff
	v_readlane_b32 s6, v254, 2
	v_readlane_b32 s7, v254, 3
	v_readlane_b32 s8, v254, 4
	v_readlane_b32 s9, v254, 5
	v_readlane_b32 s10, v254, 6
	v_readlane_b32 s11, v254, 7
	v_readlane_b32 s12, v254, 8
	v_readlane_b32 s13, v254, 9
	v_readlane_b32 s14, v254, 10
	v_readlane_b32 s15, v254, 11
	v_readlane_b32 s16, v254, 12
	v_readlane_b32 s17, v254, 13
	v_readlane_b32 s18, v254, 14
	v_readlane_b32 s19, v254, 15
	s_waitcnt vmcnt(16)
	v_fmac_f32_e32 v67, v50, v69
	v_add_f32_e32 v50, 0, v58
	s_waitcnt vmcnt(15)
	v_fmac_f32_e32 v161, v51, v69
	s_waitcnt vmcnt(14)
	v_fmac_f32_e32 v162, v52, v69
	s_waitcnt vmcnt(13)
	v_fmac_f32_e32 v163, v53, v69
	s_waitcnt vmcnt(12)
	v_fmac_f32_e32 v164, v54, v69
	s_waitcnt vmcnt(11)
	v_fmac_f32_e32 v165, v55, v69
	s_waitcnt vmcnt(10)
	v_fmac_f32_e32 v166, v56, v69
	s_waitcnt vmcnt(8)
	v_fmac_f32_e32 v168, v50, v69
	v_add_f32_e32 v50, 0, v59
	v_fmac_f32_e32 v167, v57, v69
	s_waitcnt vmcnt(7)
	v_fmac_f32_e32 v169, v50, v69
	v_add_f32_e32 v50, 0, v60
	global_store_dword v[72:73], v67, off
	global_store_dword v[76:77], v161, off
	global_store_dword v[78:79], v162, off
	global_store_dword v[80:81], v163, off
	global_store_dword v[82:83], v164, off
	global_store_dword v[84:85], v165, off
	global_store_dword v[86:87], v166, off
	global_store_dword v[88:89], v167, off
	s_waitcnt vmcnt(14)
	v_fmac_f32_e32 v170, v50, v69
	v_add_f32_e32 v50, 0, v61
	v_add_f32_e32 v67, 0, v65
	s_waitcnt vmcnt(13)
	v_fmac_f32_e32 v171, v50, v69
	v_add_f32_e32 v50, 0, v62
	global_store_dword v[144:145], v168, off
	s_waitcnt vmcnt(13)
	v_fmac_f32_e32 v172, v50, v69
	v_add_f32_e32 v50, 0, v63
	global_store_dword v[146:147], v169, off
	s_waitcnt vmcnt(13)
	v_fmac_f32_e32 v173, v50, v69
	v_add_f32_e32 v50, 0, v64
	global_store_dword v[148:149], v170, off
	global_store_dword v[150:151], v171, off
	s_waitcnt vmcnt(13)
	v_fmac_f32_e32 v174, v50, v69
	v_lshl_add_u64 v[50:51], v[74:75], 0, s[0:1]
	v_add_u32_e32 v74, v160, v176
	global_store_dword v[152:153], v172, off
	global_store_dword v[154:155], v173, off
	global_store_dword v[156:157], v174, off
	v_lshl_add_u64 v[52:53], v[50:51], 0, v[96:97]
	s_waitcnt vmcnt(15)
	v_fmac_f32_e32 v175, v67, v69
	v_ashrrev_i32_e32 v75, 31, v74
	v_lshl_add_u64 v[54:55], v[50:51], 0, v[98:99]
	v_lshl_add_u64 v[56:57], v[50:51], 0, v[100:101]
	v_lshl_add_u64 v[58:59], v[50:51], 0, v[102:103]
	v_lshl_add_u64 v[60:61], v[50:51], 0, v[104:105]
	v_lshl_add_u64 v[62:63], v[50:51], 0, v[106:107]
	v_lshl_add_u64 v[64:65], v[50:51], 0, v[108:109]
	global_load_dword v88, v[52:53], off
	global_load_dword v89, v[54:55], off
	global_load_dword v144, v[56:57], off
	global_load_dword v145, v[58:59], off
	global_load_dword v146, v[60:61], off
	global_load_dword v147, v[62:63], off
	global_load_dword v148, v[64:65], off
	v_lshl_add_u64 v[74:75], v[74:75], 2, s[28:29]
	global_store_dword v[158:159], v175, off
	global_load_dword v67, v[74:75], off
	v_lshl_add_u64 v[74:75], v[50:51], 0, v[110:111]
	global_load_dword v69, v[74:75], off
	v_lshl_add_u64 v[76:77], v[50:51], 0, v[112:113]
	global_load_dword v149, v[76:77], off
	v_lshl_add_u64 v[78:79], v[50:51], 0, v[114:115]
	global_load_dword v150, v[78:79], off
	v_lshl_add_u64 v[80:81], v[50:51], 0, v[116:117]
	global_load_dword v151, v[80:81], off
	v_lshl_add_u64 v[82:83], v[50:51], 0, v[118:119]
	global_load_dword v152, v[82:83], off
	v_lshl_add_u64 v[84:85], v[50:51], 0, v[120:121]
	global_load_dword v153, v[84:85], off
	v_lshl_add_u64 v[86:87], v[50:51], 0, v[122:123]
	global_load_dword v154, v[86:87], off
	v_lshl_add_u64 v[50:51], v[50:51], 0, v[124:125]
	global_load_dword v155, v[50:51], off
	s_waitcnt vmcnt(8)
	v_fmac_f32_e32 v177, v34, v67
	v_add_f32_e32 v34, 0, v42
	s_waitcnt vmcnt(7)
	v_fmac_f32_e32 v69, v34, v67
	v_add_f32_e32 v34, 0, v43
	s_waitcnt vmcnt(6)
	v_fmac_f32_e32 v149, v34, v67
	v_add_f32_e32 v34, 0, v44
	s_waitcnt vmcnt(5)
	v_fmac_f32_e32 v150, v34, v67
	v_add_f32_e32 v34, 0, v45
	s_waitcnt vmcnt(4)
	v_fmac_f32_e32 v151, v34, v67
	v_add_f32_e32 v34, 0, v46
	s_waitcnt vmcnt(3)
	v_fmac_f32_e32 v152, v34, v67
	v_add_f32_e32 v34, 0, v47
	s_waitcnt vmcnt(2)
	v_fmac_f32_e32 v153, v34, v67
	v_add_f32_e32 v34, 0, v48
	s_waitcnt vmcnt(1)
	v_fmac_f32_e32 v154, v34, v67
	v_add_f32_e32 v34, 0, v49
	s_waitcnt vmcnt(0)
	v_fmac_f32_e32 v155, v34, v67
	v_or_b32_e32 v34, 32, v68
	v_cmp_lt_i32_e32 vcc, s50, v34
	v_fmac_f32_e32 v88, v35, v67
	v_ashrrev_i32_e32 v35, 31, v34
	v_cndmask_b32_e32 v0, 0, v0, vcc
	v_fmac_f32_e32 v89, v36, v67
	v_lshlrev_b64 v[34:35], 12, v[34:35]
	v_add_u32_e32 v36, v0, v66
	v_fmac_f32_e32 v144, v37, v67
	v_fmac_f32_e32 v148, v41, v67
	v_lshl_add_u64 v[34:35], s[4:5], 0, v[34:35]
	v_ashrrev_i32_e32 v37, 31, v36
	v_fmac_f32_e32 v145, v38, v67
	v_fmac_f32_e32 v146, v39, v67
	v_fmac_f32_e32 v147, v40, v67
	global_store_dword v[72:73], v177, off offset:128
	global_store_dword v[52:53], v88, off
	global_store_dword v[54:55], v89, off
	global_store_dword v[56:57], v144, off
	global_store_dword v[58:59], v145, off
	global_store_dword v[60:61], v146, off
	global_store_dword v[62:63], v147, off
	global_store_dword v[64:65], v148, off
	global_store_dword v[74:75], v69, off
	global_store_dword v[76:77], v149, off
	global_store_dword v[78:79], v150, off
	global_store_dword v[80:81], v151, off
	global_store_dword v[82:83], v152, off
	global_store_dword v[84:85], v153, off
	global_store_dword v[86:87], v154, off
	global_store_dword v[50:51], v155, off
	v_lshl_add_u64 v[36:37], v[36:37], 2, s[28:29]
	v_lshl_add_u64 v[34:35], v[34:35], 0, v[70:71]
	global_load_dword v68, v[36:37], off
	v_lshl_add_u64 v[36:37], v[34:35], 0, v[94:95]
	v_lshl_add_u64 v[44:45], v[34:35], 0, v[102:103]
	v_lshl_add_u64 v[38:39], v[34:35], 0, v[96:97]
	v_lshl_add_u64 v[40:41], v[34:35], 0, v[98:99]
	v_lshl_add_u64 v[42:43], v[34:35], 0, v[100:101]
	global_load_dword v69, v[36:37], off
	global_load_dword v70, v[38:39], off
	global_load_dword v71, v[40:41], off
	global_load_dword v72, v[42:43], off
	global_load_dword v73, v[44:45], off
	v_lshl_add_u64 v[46:47], v[34:35], 0, v[104:105]
	global_load_dword v74, v[46:47], off
	v_lshl_add_u64 v[48:49], v[34:35], 0, v[106:107]
	global_load_dword v75, v[48:49], off
	v_lshl_add_u64 v[50:51], v[34:35], 0, v[108:109]
	global_load_dword v76, v[50:51], off
	v_lshl_add_u64 v[52:53], v[34:35], 0, v[110:111]
	global_load_dword v77, v[52:53], off
	v_lshl_add_u64 v[54:55], v[34:35], 0, v[112:113]
	global_load_dword v78, v[54:55], off
	v_lshl_add_u64 v[56:57], v[34:35], 0, v[114:115]
	global_load_dword v79, v[56:57], off
	global_load_dword v85, v[36:37], off offset:128
	v_lshl_add_u64 v[58:59], v[34:35], 0, v[116:117]
	global_load_dword v80, v[58:59], off
	v_lshl_add_u64 v[60:61], v[34:35], 0, v[118:119]
	global_load_dword v81, v[60:61], off
	v_lshl_add_u64 v[62:63], v[34:35], 0, v[120:121]
	global_load_dword v82, v[62:63], off
	v_lshl_add_u64 v[64:65], v[34:35], 0, v[122:123]
	global_load_dword v83, v[64:65], off
	v_lshl_add_u64 v[66:67], v[34:35], 0, v[124:125]
	global_load_dword v84, v[66:67], off
	s_waitcnt vmcnt(16)
	v_fmac_f32_e32 v69, v18, v68
	v_add_f32_e32 v18, 0, v22
	s_waitcnt vmcnt(15)
	v_fmac_f32_e32 v70, v19, v68
	s_waitcnt vmcnt(14)
	v_fmac_f32_e32 v71, v20, v68
	s_waitcnt vmcnt(12)
	v_fmac_f32_e32 v73, v18, v68
	v_add_f32_e32 v18, 0, v23
	s_waitcnt vmcnt(11)
	v_fmac_f32_e32 v74, v18, v68
	v_add_f32_e32 v18, 0, v24
	s_waitcnt vmcnt(10)
	v_fmac_f32_e32 v75, v18, v68
	v_add_f32_e32 v18, 0, v25
	s_waitcnt vmcnt(9)
	v_fmac_f32_e32 v76, v18, v68
	v_add_f32_e32 v18, 0, v26
	s_waitcnt vmcnt(8)
	v_fmac_f32_e32 v77, v18, v68
	v_add_f32_e32 v18, 0, v27
	s_waitcnt vmcnt(7)
	v_fmac_f32_e32 v78, v18, v68
	v_add_f32_e32 v18, 0, v28
	s_waitcnt vmcnt(6)
	v_fmac_f32_e32 v79, v18, v68
	v_add_f32_e32 v18, 0, v29
	v_fmac_f32_e32 v72, v21, v68
	s_waitcnt vmcnt(4)
	v_fmac_f32_e32 v80, v18, v68
	v_add_f32_e32 v18, 0, v30
	s_waitcnt vmcnt(3)
	v_fmac_f32_e32 v81, v18, v68
	v_add_f32_e32 v18, 0, v31
	s_waitcnt vmcnt(2)
	v_fmac_f32_e32 v82, v18, v68
	v_add_f32_e32 v18, 0, v32
	global_store_dword v[36:37], v69, off
	global_store_dword v[38:39], v70, off
	global_store_dword v[40:41], v71, off
	global_store_dword v[42:43], v72, off
	s_waitcnt vmcnt(5)
	v_fmac_f32_e32 v83, v18, v68
	v_add_f32_e32 v38, 0, v33
	v_lshl_add_u64 v[18:19], v[34:35], 0, s[0:1]
	v_add_u32_e32 v34, v0, v176
	global_store_dword v[44:45], v73, off
	global_store_dword v[46:47], v74, off
	global_store_dword v[48:49], v75, off
	global_store_dword v[50:51], v76, off
	global_store_dword v[52:53], v77, off
	global_store_dword v[54:55], v78, off
	global_store_dword v[56:57], v79, off
	global_store_dword v[58:59], v80, off
	global_store_dword v[60:61], v81, off
	global_store_dword v[62:63], v82, off
	global_store_dword v[64:65], v83, off
	v_lshl_add_u64 v[20:21], v[18:19], 0, v[96:97]
	s_waitcnt vmcnt(15)
	v_fmac_f32_e32 v84, v38, v68
	v_ashrrev_i32_e32 v35, 31, v34
	v_lshl_add_u64 v[22:23], v[18:19], 0, v[98:99]
	v_lshl_add_u64 v[24:25], v[18:19], 0, v[100:101]
	v_lshl_add_u64 v[26:27], v[18:19], 0, v[102:103]
	v_lshl_add_u64 v[28:29], v[18:19], 0, v[104:105]
	v_lshl_add_u64 v[30:31], v[18:19], 0, v[106:107]
	v_lshl_add_u64 v[32:33], v[18:19], 0, v[108:109]
	global_load_dword v50, v[20:21], off
	global_load_dword v51, v[22:23], off
	global_load_dword v52, v[24:25], off
	global_load_dword v53, v[26:27], off
	global_load_dword v54, v[28:29], off
	global_load_dword v55, v[30:31], off
	global_load_dword v56, v[32:33], off
	v_lshl_add_u64 v[34:35], v[34:35], 2, s[28:29]
	global_store_dword v[66:67], v84, off
	global_load_dword v0, v[34:35], off
	v_lshl_add_u64 v[34:35], v[18:19], 0, v[110:111]
	global_load_dword v57, v[34:35], off
	v_lshl_add_u64 v[38:39], v[18:19], 0, v[112:113]
	global_load_dword v58, v[38:39], off
	v_lshl_add_u64 v[40:41], v[18:19], 0, v[114:115]
	global_load_dword v59, v[40:41], off
	v_lshl_add_u64 v[42:43], v[18:19], 0, v[116:117]
	global_load_dword v60, v[42:43], off
	v_lshl_add_u64 v[44:45], v[18:19], 0, v[118:119]
	global_load_dword v61, v[44:45], off
	v_lshl_add_u64 v[46:47], v[18:19], 0, v[120:121]
	global_load_dword v62, v[46:47], off
	v_lshl_add_u64 v[48:49], v[18:19], 0, v[122:123]
	global_load_dword v63, v[48:49], off
	v_lshl_add_u64 v[18:19], v[18:19], 0, v[124:125]
	global_load_dword v64, v[18:19], off
	s_waitcnt vmcnt(8)
	v_fmac_f32_e32 v85, v2, v0
	v_add_f32_e32 v2, 0, v6
	v_fmac_f32_e32 v53, v2, v0
	v_add_f32_e32 v2, 0, v7
	v_fmac_f32_e32 v54, v2, v0
	v_add_f32_e32 v2, 0, v8
	v_fmac_f32_e32 v55, v2, v0
	v_add_f32_e32 v2, 0, v9
	v_fmac_f32_e32 v56, v2, v0
	v_add_f32_e32 v2, 0, v10
	s_waitcnt vmcnt(7)
	v_fmac_f32_e32 v57, v2, v0
	v_add_f32_e32 v2, 0, v11
	s_waitcnt vmcnt(6)
	v_fmac_f32_e32 v58, v2, v0
	v_add_f32_e32 v2, 0, v12
	s_waitcnt vmcnt(5)
	v_fmac_f32_e32 v59, v2, v0
	v_add_f32_e32 v2, 0, v13
	s_waitcnt vmcnt(4)
	v_fmac_f32_e32 v60, v2, v0
	v_add_f32_e32 v2, 0, v14
	s_waitcnt vmcnt(3)
	v_fmac_f32_e32 v61, v2, v0
	v_add_f32_e32 v2, 0, v15
	s_waitcnt vmcnt(2)
	v_fmac_f32_e32 v62, v2, v0
	v_add_f32_e32 v2, 0, v16
	s_waitcnt vmcnt(1)
	v_fmac_f32_e32 v63, v2, v0
	v_add_f32_e32 v2, 0, v17
	s_waitcnt vmcnt(0)
	v_fmac_f32_e32 v64, v2, v0
	v_fmac_f32_e32 v50, v3, v0
	v_fmac_f32_e32 v51, v4, v0
	v_fmac_f32_e32 v52, v5, v0
	global_store_dword v[36:37], v85, off offset:128
	global_store_dword v[20:21], v50, off
	global_store_dword v[22:23], v51, off
	global_store_dword v[24:25], v52, off
	global_store_dword v[26:27], v53, off
	global_store_dword v[28:29], v54, off
	global_store_dword v[30:31], v55, off
	global_store_dword v[32:33], v56, off
	global_store_dword v[34:35], v57, off
	global_store_dword v[38:39], v58, off
	global_store_dword v[40:41], v59, off
	global_store_dword v[42:43], v60, off
	global_store_dword v[44:45], v61, off
	global_store_dword v[46:47], v62, off
	global_store_dword v[48:49], v63, off
	global_store_dword v[18:19], v64, off
	s_cbranch_scc0 .LBB0_954
